# compensation barrier of the older half moved behind the first epilogue stores / load issues in all GEMM phases
# baseline (speedup 1.0000x reference)
.Lrwp3a_exit:
.LBB0_563:
	s_lshl_b32 s98, s64, 8
	s_add_i32 s98, s98, s80
	s_lshl_b32 s98, s98, 11
	s_lshl_b32 s99, s91, 8
	s_or_b32 s99, s99, s81
	s_lshl_b32 s99, s99, 1
	s_add_u32 s98, s98, s99
	s_add_u32 s98, s44, s98
	s_addc_u32 s99, s45, 0
	v_lshlrev_b32_e32 v146, 11, v1
	v_lshl_add_u32 v146, v148, 4, v146
	global_load_dwordx4 v[154:157], v146, s[98:99]
	global_load_dwordx4 v[158:161], v146, s[98:99] offset:256
	s_add_u32 s98, s98, 0x8000
	s_addc_u32 s99, s99, 0
	global_load_dwordx4 v[162:165], v146, s[98:99]
	global_load_dwordx4 v[166:169], v146, s[98:99] offset:256
	s_add_u32 s98, s98, 0x8000
	s_addc_u32 s99, s99, 0
	global_load_dwordx4 v[170:173], v146, s[98:99]
	global_load_dwordx4 v[174:177], v146, s[98:99] offset:256
	s_add_u32 s98, s98, 0x8000
	s_addc_u32 s99, s99, 0
	global_load_dwordx4 v[178:181], v146, s[98:99]
	global_load_dwordx4 v[182:185], v146, s[98:99] offset:256
	s_add_u32 s98, s98, 0x28000
	s_addc_u32 s99, s99, 0
	global_load_dwordx4 v[186:189], v146, s[98:99]
	global_load_dwordx4 v[190:193], v146, s[98:99] offset:256
	s_add_u32 s98, s98, 0x8000
	s_addc_u32 s99, s99, 0
	global_load_dwordx4 v[194:197], v146, s[98:99]
	global_load_dwordx4 v[198:201], v146, s[98:99] offset:256
	s_add_u32 s98, s98, 0x8000
	s_addc_u32 s99, s99, 0
	global_load_dwordx4 v[202:205], v146, s[98:99]
	global_load_dwordx4 v[206:209], v146, s[98:99] offset:256
	s_add_u32 s98, s98, 0x8000
	s_addc_u32 s99, s99, 0
	global_load_dwordx4 v[210:213], v146, s[98:99]
	global_load_dwordx4 v[214:217], v146, s[98:99] offset:256
	s_and_b64 vcc, exec, s[20:21]
	s_cbranch_vccz .Lepi3a_nobar
	s_barrier
.Lepi3a_nobar:
	s_waitcnt vmcnt(15)
	v_lshlrev_b32_e32 v218, 16, v154
	v_and_b32_e32 v154, 0xffff0000, v154
	v_lshlrev_b32_e32 v219, 16, v155
	v_and_b32_e32 v155, 0xffff0000, v155
	v_lshlrev_b32_e32 v220, 16, v156
	v_and_b32_e32 v156, 0xffff0000, v156
	v_lshlrev_b32_e32 v221, 16, v157
	v_and_b32_e32 v157, 0xffff0000, v157
	v_mul_f32_e32 v126, v126, v218
	v_mul_f32_e32 v127, v127, v154
	v_mul_f32_e32 v128, v128, v219
	v_mul_f32_e32 v129, v129, v155
	v_mul_f32_e32 v122, v122, v220
	v_mul_f32_e32 v123, v123, v156
	v_mul_f32_e32 v124, v124, v221
	v_mul_f32_e32 v125, v125, v157
	v_cvt_pk_bf16_f32 v154, v126, v127
	v_cvt_pk_bf16_f32 v155, v128, v129
	v_cvt_pk_bf16_f32 v156, v122, v123
	v_cvt_pk_bf16_f32 v157, v124, v125
	s_sub_u32 s98, s98, 0x58000
	s_subb_u32 s99, s99, 0
	global_store_dwordx4 v146, v[154:157], s[98:99] nt
	s_waitcnt vmcnt(15)
	v_lshlrev_b32_e32 v218, 16, v158
	v_and_b32_e32 v158, 0xffff0000, v158
	v_lshlrev_b32_e32 v219, 16, v159
	v_and_b32_e32 v159, 0xffff0000, v159
	v_lshlrev_b32_e32 v220, 16, v160
	v_and_b32_e32 v160, 0xffff0000, v160
	v_lshlrev_b32_e32 v221, 16, v161
	v_and_b32_e32 v161, 0xffff0000, v161
	v_mul_f32_e32 v118, v118, v218
	v_mul_f32_e32 v119, v119, v158
	v_mul_f32_e32 v120, v120, v219
	v_mul_f32_e32 v121, v121, v159
	v_mul_f32_e32 v110, v110, v220
	v_mul_f32_e32 v111, v111, v160
	v_mul_f32_e32 v112, v112, v221
	v_mul_f32_e32 v113, v113, v161
	v_cvt_pk_bf16_f32 v158, v118, v119
	v_cvt_pk_bf16_f32 v159, v120, v121
	v_cvt_pk_bf16_f32 v160, v110, v111
	v_cvt_pk_bf16_f32 v161, v112, v113
	global_store_dwordx4 v146, v[158:161], s[98:99] offset:256 nt
	s_waitcnt vmcnt(15)
	v_lshlrev_b32_e32 v218, 16, v162
	v_and_b32_e32 v162, 0xffff0000, v162
	v_lshlrev_b32_e32 v219, 16, v163
	v_and_b32_e32 v163, 0xffff0000, v163
	v_lshlrev_b32_e32 v220, 16, v164
	v_and_b32_e32 v164, 0xffff0000, v164
	v_lshlrev_b32_e32 v221, 16, v165
	v_and_b32_e32 v165, 0xffff0000, v165
	v_mul_f32_e32 v114, v114, v218
	v_mul_f32_e32 v115, v115, v162
	v_mul_f32_e32 v116, v116, v219
	v_mul_f32_e32 v117, v117, v163
	v_mul_f32_e32 v106, v106, v220
	v_mul_f32_e32 v107, v107, v164
	v_mul_f32_e32 v108, v108, v221
	v_mul_f32_e32 v109, v109, v165
	v_cvt_pk_bf16_f32 v162, v114, v115
	v_cvt_pk_bf16_f32 v163, v116, v117
	v_cvt_pk_bf16_f32 v164, v106, v107
	v_cvt_pk_bf16_f32 v165, v108, v109
	s_add_u32 s98, s98, 0x8000
	s_addc_u32 s99, s99, 0
	global_store_dwordx4 v146, v[162:165], s[98:99] nt
	s_waitcnt vmcnt(15)
	v_lshlrev_b32_e32 v218, 16, v166
	v_and_b32_e32 v166, 0xffff0000, v166
	v_lshlrev_b32_e32 v219, 16, v167
	v_and_b32_e32 v167, 0xffff0000, v167
	v_lshlrev_b32_e32 v220, 16, v168
	v_and_b32_e32 v168, 0xffff0000, v168
	v_lshlrev_b32_e32 v221, 16, v169
	v_and_b32_e32 v169, 0xffff0000, v169
	v_mul_f32_e32 v102, v102, v218
	v_mul_f32_e32 v103, v103, v166
	v_mul_f32_e32 v104, v104, v219
	v_mul_f32_e32 v105, v105, v167
	v_mul_f32_e32 v94, v94, v220
	v_mul_f32_e32 v95, v95, v168
	v_mul_f32_e32 v96, v96, v221
	v_mul_f32_e32 v97, v97, v169
	v_cvt_pk_bf16_f32 v166, v102, v103
	v_cvt_pk_bf16_f32 v167, v104, v105
	v_cvt_pk_bf16_f32 v168, v94, v95
	v_cvt_pk_bf16_f32 v169, v96, v97
	global_store_dwordx4 v146, v[166:169], s[98:99] offset:256 nt
	s_waitcnt vmcnt(15)
	v_lshlrev_b32_e32 v218, 16, v170
	v_and_b32_e32 v170, 0xffff0000, v170
	v_lshlrev_b32_e32 v219, 16, v171
	v_and_b32_e32 v171, 0xffff0000, v171
	v_lshlrev_b32_e32 v220, 16, v172
	v_and_b32_e32 v172, 0xffff0000, v172
	v_lshlrev_b32_e32 v221, 16, v173
	v_and_b32_e32 v173, 0xffff0000, v173
	v_mul_f32_e32 v98, v98, v218
	v_mul_f32_e32 v99, v99, v170
	v_mul_f32_e32 v100, v100, v219
	v_mul_f32_e32 v101, v101, v171
	v_mul_f32_e32 v90, v90, v220
	v_mul_f32_e32 v91, v91, v172
	v_mul_f32_e32 v92, v92, v221
	v_mul_f32_e32 v93, v93, v173
	v_cvt_pk_bf16_f32 v170, v98, v99
	v_cvt_pk_bf16_f32 v171, v100, v101
	v_cvt_pk_bf16_f32 v172, v90, v91
	v_cvt_pk_bf16_f32 v173, v92, v93
	s_add_u32 s98, s98, 0x8000
	s_addc_u32 s99, s99, 0
	global_store_dwordx4 v146, v[170:173], s[98:99] nt
	s_waitcnt vmcnt(15)
	v_lshlrev_b32_e32 v218, 16, v174
	v_and_b32_e32 v174, 0xffff0000, v174
	v_lshlrev_b32_e32 v219, 16, v175
	v_and_b32_e32 v175, 0xffff0000, v175
	v_lshlrev_b32_e32 v220, 16, v176
	v_and_b32_e32 v176, 0xffff0000, v176
	v_lshlrev_b32_e32 v221, 16, v177
	v_and_b32_e32 v177, 0xffff0000, v177
	v_mul_f32_e32 v86, v86, v218
	v_mul_f32_e32 v87, v87, v174
	v_mul_f32_e32 v88, v88, v219
	v_mul_f32_e32 v89, v89, v175
	v_mul_f32_e32 v78, v78, v220
	v_mul_f32_e32 v79, v79, v176
	v_mul_f32_e32 v80, v80, v221
	v_mul_f32_e32 v81, v81, v177
	v_cvt_pk_bf16_f32 v174, v86, v87
	v_cvt_pk_bf16_f32 v175, v88, v89
	v_cvt_pk_bf16_f32 v176, v78, v79
	v_cvt_pk_bf16_f32 v177, v80, v81
	global_store_dwordx4 v146, v[174:177], s[98:99] offset:256 nt
	s_waitcnt vmcnt(15)
	v_lshlrev_b32_e32 v218, 16, v178
	v_and_b32_e32 v178, 0xffff0000, v178
	v_lshlrev_b32_e32 v219, 16, v179
	v_and_b32_e32 v179, 0xffff0000, v179
	v_lshlrev_b32_e32 v220, 16, v180
	v_and_b32_e32 v180, 0xffff0000, v180
	v_lshlrev_b32_e32 v221, 16, v181
	v_and_b32_e32 v181, 0xffff0000, v181
	v_mul_f32_e32 v82, v82, v218
	v_mul_f32_e32 v83, v83, v178
	v_mul_f32_e32 v84, v84, v219
	v_mul_f32_e32 v85, v85, v179
	v_mul_f32_e32 v74, v74, v220
	v_mul_f32_e32 v75, v75, v180
	v_mul_f32_e32 v76, v76, v221
	v_mul_f32_e32 v77, v77, v181
	v_cvt_pk_bf16_f32 v178, v82, v83
	v_cvt_pk_bf16_f32 v179, v84, v85
	v_cvt_pk_bf16_f32 v180, v74, v75
	v_cvt_pk_bf16_f32 v181, v76, v77
	s_add_u32 s98, s98, 0x8000
	s_addc_u32 s99, s99, 0
	global_store_dwordx4 v146, v[178:181], s[98:99] nt
	s_waitcnt vmcnt(15)
	v_lshlrev_b32_e32 v218, 16, v182
	v_and_b32_e32 v182, 0xffff0000, v182
	v_lshlrev_b32_e32 v219, 16, v183
	v_and_b32_e32 v183, 0xffff0000, v183
	v_lshlrev_b32_e32 v220, 16, v184
	v_and_b32_e32 v184, 0xffff0000, v184
	v_lshlrev_b32_e32 v221, 16, v185
	v_and_b32_e32 v185, 0xffff0000, v185
	v_mul_f32_e32 v70, v70, v218
	v_mul_f32_e32 v71, v71, v182
	v_mul_f32_e32 v72, v72, v219
	v_mul_f32_e32 v73, v73, v183
	v_mul_f32_e32 v66, v66, v220
	v_mul_f32_e32 v67, v67, v184
	v_mul_f32_e32 v68, v68, v221
	v_mul_f32_e32 v69, v69, v185
	v_cvt_pk_bf16_f32 v182, v70, v71
	v_cvt_pk_bf16_f32 v183, v72, v73
	v_cvt_pk_bf16_f32 v184, v66, v67
	v_cvt_pk_bf16_f32 v185, v68, v69
	global_store_dwordx4 v146, v[182:185], s[98:99] offset:256 nt
	s_waitcnt vmcnt(15)
	v_lshlrev_b32_e32 v218, 16, v186
	v_and_b32_e32 v186, 0xffff0000, v186
	v_lshlrev_b32_e32 v219, 16, v187
	v_and_b32_e32 v187, 0xffff0000, v187
	v_lshlrev_b32_e32 v220, 16, v188
	v_and_b32_e32 v188, 0xffff0000, v188
	v_lshlrev_b32_e32 v221, 16, v189
	v_and_b32_e32 v189, 0xffff0000, v189
	v_mul_f32_e32 v62, v62, v218
	v_mul_f32_e32 v63, v63, v186
	v_mul_f32_e32 v64, v64, v219
	v_mul_f32_e32 v65, v65, v187
	v_mul_f32_e32 v58, v58, v220
	v_mul_f32_e32 v59, v59, v188
	v_mul_f32_e32 v60, v60, v221
	v_mul_f32_e32 v61, v61, v189
	v_cvt_pk_bf16_f32 v186, v62, v63
	v_cvt_pk_bf16_f32 v187, v64, v65
	v_cvt_pk_bf16_f32 v188, v58, v59
	v_cvt_pk_bf16_f32 v189, v60, v61
	s_add_u32 s98, s98, 0x28000
	s_addc_u32 s99, s99, 0
	global_store_dwordx4 v146, v[186:189], s[98:99] nt
	s_waitcnt vmcnt(15)
	v_lshlrev_b32_e32 v218, 16, v190
	v_and_b32_e32 v190, 0xffff0000, v190
	v_lshlrev_b32_e32 v219, 16, v191
	v_and_b32_e32 v191, 0xffff0000, v191
	v_lshlrev_b32_e32 v220, 16, v192
	v_and_b32_e32 v192, 0xffff0000, v192
	v_lshlrev_b32_e32 v221, 16, v193
	v_and_b32_e32 v193, 0xffff0000, v193
	v_mul_f32_e32 v54, v54, v218
	v_mul_f32_e32 v55, v55, v190
	v_mul_f32_e32 v56, v56, v219
	v_mul_f32_e32 v57, v57, v191
	v_mul_f32_e32 v46, v46, v220
	v_mul_f32_e32 v47, v47, v192
	v_mul_f32_e32 v48, v48, v221
	v_mul_f32_e32 v49, v49, v193
	v_cvt_pk_bf16_f32 v190, v54, v55
	v_cvt_pk_bf16_f32 v191, v56, v57
	v_cvt_pk_bf16_f32 v192, v46, v47
	v_cvt_pk_bf16_f32 v193, v48, v49
	global_store_dwordx4 v146, v[190:193], s[98:99] offset:256 nt
	s_waitcnt vmcnt(15)
	v_lshlrev_b32_e32 v218, 16, v194
	v_and_b32_e32 v194, 0xffff0000, v194
	v_lshlrev_b32_e32 v219, 16, v195
	v_and_b32_e32 v195, 0xffff0000, v195
	v_lshlrev_b32_e32 v220, 16, v196
	v_and_b32_e32 v196, 0xffff0000, v196
	v_lshlrev_b32_e32 v221, 16, v197
	v_and_b32_e32 v197, 0xffff0000, v197
	v_mul_f32_e32 v50, v50, v218
	v_mul_f32_e32 v51, v51, v194
	v_mul_f32_e32 v52, v52, v219
	v_mul_f32_e32 v53, v53, v195
	v_mul_f32_e32 v42, v42, v220
	v_mul_f32_e32 v43, v43, v196
	v_mul_f32_e32 v44, v44, v221
	v_mul_f32_e32 v45, v45, v197
	v_cvt_pk_bf16_f32 v194, v50, v51
	v_cvt_pk_bf16_f32 v195, v52, v53
	v_cvt_pk_bf16_f32 v196, v42, v43
	v_cvt_pk_bf16_f32 v197, v44, v45
	s_add_u32 s98, s98, 0x8000
	s_addc_u32 s99, s99, 0
	global_store_dwordx4 v146, v[194:197], s[98:99] nt
	s_waitcnt vmcnt(15)
	v_lshlrev_b32_e32 v218, 16, v198
	v_and_b32_e32 v198, 0xffff0000, v198
	v_lshlrev_b32_e32 v219, 16, v199
	v_and_b32_e32 v199, 0xffff0000, v199
	v_lshlrev_b32_e32 v220, 16, v200
	v_and_b32_e32 v200, 0xffff0000, v200
	v_lshlrev_b32_e32 v221, 16, v201
	v_and_b32_e32 v201, 0xffff0000, v201
	v_mul_f32_e32 v38, v38, v218
	v_mul_f32_e32 v39, v39, v198
	v_mul_f32_e32 v40, v40, v219
	v_mul_f32_e32 v41, v41, v199
	v_mul_f32_e32 v30, v30, v220
	v_mul_f32_e32 v31, v31, v200
	v_mul_f32_e32 v32, v32, v221
	v_mul_f32_e32 v33, v33, v201
	v_cvt_pk_bf16_f32 v198, v38, v39
	v_cvt_pk_bf16_f32 v199, v40, v41
	v_cvt_pk_bf16_f32 v200, v30, v31
	v_cvt_pk_bf16_f32 v201, v32, v33
	global_store_dwordx4 v146, v[198:201], s[98:99] offset:256 nt
	s_waitcnt vmcnt(15)
	v_lshlrev_b32_e32 v218, 16, v202
	v_and_b32_e32 v202, 0xffff0000, v202
	v_lshlrev_b32_e32 v219, 16, v203
	v_and_b32_e32 v203, 0xffff0000, v203
	v_lshlrev_b32_e32 v220, 16, v204
	v_and_b32_e32 v204, 0xffff0000, v204
	v_lshlrev_b32_e32 v221, 16, v205
	v_and_b32_e32 v205, 0xffff0000, v205
	v_mul_f32_e32 v34, v34, v218
	v_mul_f32_e32 v35, v35, v202
	v_mul_f32_e32 v36, v36, v219
	v_mul_f32_e32 v37, v37, v203
	v_mul_f32_e32 v26, v26, v220
	v_mul_f32_e32 v27, v27, v204
	v_mul_f32_e32 v28, v28, v221
	v_mul_f32_e32 v29, v29, v205
	v_cvt_pk_bf16_f32 v202, v34, v35
	v_cvt_pk_bf16_f32 v203, v36, v37
	v_cvt_pk_bf16_f32 v204, v26, v27
	v_cvt_pk_bf16_f32 v205, v28, v29
	s_add_u32 s98, s98, 0x8000
	s_addc_u32 s99, s99, 0
	global_store_dwordx4 v146, v[202:205], s[98:99] nt
	s_waitcnt vmcnt(15)
	v_lshlrev_b32_e32 v218, 16, v206
	v_and_b32_e32 v206, 0xffff0000, v206
	v_lshlrev_b32_e32 v219, 16, v207
	v_and_b32_e32 v207, 0xffff0000, v207
	v_lshlrev_b32_e32 v220, 16, v208
	v_and_b32_e32 v208, 0xffff0000, v208
	v_lshlrev_b32_e32 v221, 16, v209
	v_and_b32_e32 v209, 0xffff0000, v209
	v_mul_f32_e32 v22, v22, v218
	v_mul_f32_e32 v23, v23, v206
	v_mul_f32_e32 v24, v24, v219
	v_mul_f32_e32 v25, v25, v207
	v_mul_f32_e32 v14, v14, v220
	v_mul_f32_e32 v15, v15, v208
	v_mul_f32_e32 v16, v16, v221
	v_mul_f32_e32 v17, v17, v209
	v_cvt_pk_bf16_f32 v206, v22, v23
	v_cvt_pk_bf16_f32 v207, v24, v25
	v_cvt_pk_bf16_f32 v208, v14, v15
	v_cvt_pk_bf16_f32 v209, v16, v17
	global_store_dwordx4 v146, v[206:209], s[98:99] offset:256 nt
	s_waitcnt vmcnt(15)
	v_lshlrev_b32_e32 v218, 16, v210
	v_and_b32_e32 v210, 0xffff0000, v210
	v_lshlrev_b32_e32 v219, 16, v211
	v_and_b32_e32 v211, 0xffff0000, v211
	v_lshlrev_b32_e32 v220, 16, v212
	v_and_b32_e32 v212, 0xffff0000, v212
	v_lshlrev_b32_e32 v221, 16, v213
	v_and_b32_e32 v213, 0xffff0000, v213
	v_mul_f32_e32 v18, v18, v218
	v_mul_f32_e32 v19, v19, v210
	v_mul_f32_e32 v20, v20, v219
	v_mul_f32_e32 v21, v21, v211
	v_mul_f32_e32 v10, v10, v220
	v_mul_f32_e32 v11, v11, v212
	v_mul_f32_e32 v12, v12, v221
	v_mul_f32_e32 v13, v13, v213
	v_cvt_pk_bf16_f32 v210, v18, v19
	v_cvt_pk_bf16_f32 v211, v20, v21
	v_cvt_pk_bf16_f32 v212, v10, v11
	v_cvt_pk_bf16_f32 v213, v12, v13
	s_add_u32 s98, s98, 0x8000
	s_addc_u32 s99, s99, 0
	global_store_dwordx4 v146, v[210:213], s[98:99] nt
	s_waitcnt vmcnt(15)
	v_lshlrev_b32_e32 v218, 16, v214
	v_and_b32_e32 v214, 0xffff0000, v214
	v_lshlrev_b32_e32 v219, 16, v215
	v_and_b32_e32 v215, 0xffff0000, v215
	v_lshlrev_b32_e32 v220, 16, v216
	v_and_b32_e32 v216, 0xffff0000, v216
	v_lshlrev_b32_e32 v221, 16, v217
	v_and_b32_e32 v217, 0xffff0000, v217
	v_mul_f32_e32 v6, v6, v218
	v_mul_f32_e32 v7, v7, v214
	v_mul_f32_e32 v8, v8, v219
	v_mul_f32_e32 v9, v9, v215
	v_mul_f32_e32 v2, v2, v220
	v_mul_f32_e32 v3, v3, v216
	v_mul_f32_e32 v4, v4, v221
	v_mul_f32_e32 v5, v5, v217
	v_cvt_pk_bf16_f32 v214, v6, v7
	v_cvt_pk_bf16_f32 v215, v8, v9
	v_cvt_pk_bf16_f32 v216, v2, v3
	v_cvt_pk_bf16_f32 v217, v4, v5
	global_store_dwordx4 v146, v[214:217], s[98:99] offset:256 nt
	s_andn2_b64 vcc, exec, s[0:1]
	s_mov_b64 s[0:1], -1
	s_mov_b32 s100, 1
	s_cbranch_vccnz .LBB0_552
	s_andn2_b64 vcc, exec, s[10:11]
	s_cbranch_vccnz .LBB0_551
	s_barrier
	s_branch .LBB0_551

.Lrwp3b_exit:
.LBB0_587:
	s_lshl_b32 s98, s70, 8
	s_add_i32 s98, s98, s82
	s_lshl_b32 s98, s98, 11
	s_lshl_b32 s99, s89, 8
	s_or_b32 s99, s99, s83
	s_lshl_b32 s99, s99, 1
	s_add_u32 s98, s98, s99
	s_add_u32 s98, s44, s98
	s_addc_u32 s99, s45, 0
	v_lshlrev_b32_e32 v146, 11, v1
	v_lshl_add_u32 v146, v148, 4, v146
	v_add_u32_e32 v147, 0x8000000, v146
	global_load_dwordx4 v[154:157], v146, s[98:99]
	global_load_dwordx4 v[158:161], v147, s[98:99]
	global_load_dwordx4 v[162:165], v146, s[98:99] offset:256
	global_load_dwordx4 v[166:169], v147, s[98:99] offset:256
	s_add_u32 s98, s98, 0x8000
	s_addc_u32 s99, s99, 0
	global_load_dwordx4 v[170:173], v146, s[98:99]
	global_load_dwordx4 v[174:177], v147, s[98:99]
	global_load_dwordx4 v[178:181], v146, s[98:99] offset:256
	global_load_dwordx4 v[182:185], v147, s[98:99] offset:256
	s_add_u32 s98, s98, 0x8000
	s_addc_u32 s99, s99, 0
	global_load_dwordx4 v[186:189], v146, s[98:99]
	global_load_dwordx4 v[190:193], v147, s[98:99]
	global_load_dwordx4 v[194:197], v146, s[98:99] offset:256
	global_load_dwordx4 v[198:201], v147, s[98:99] offset:256
	s_add_u32 s98, s98, 0x8000
	s_addc_u32 s99, s99, 0
	global_load_dwordx4 v[202:205], v146, s[98:99]
	global_load_dwordx4 v[206:209], v147, s[98:99]
	global_load_dwordx4 v[210:213], v146, s[98:99] offset:256
	global_load_dwordx4 v[214:217], v147, s[98:99] offset:256
	s_and_b64 vcc, exec, s[42:43]
	s_cbranch_vccz .Lepi3b_nobar
	s_barrier
.Lepi3b_nobar:
	s_waitcnt vmcnt(14)
	v_lshlrev_b32_e32 v218, 16, v154
	v_and_b32_e32 v154, 0xffff0000, v154
	v_lshlrev_b32_e32 v219, 16, v155
	v_and_b32_e32 v155, 0xffff0000, v155
	v_lshlrev_b32_e32 v220, 16, v156
	v_and_b32_e32 v156, 0xffff0000, v156
	v_lshlrev_b32_e32 v221, 16, v157
	v_and_b32_e32 v157, 0xffff0000, v157
	v_lshlrev_b32_e32 v222, 16, v158
	v_and_b32_e32 v158, 0xffff0000, v158
	v_lshlrev_b32_e32 v223, 16, v159
	v_and_b32_e32 v159, 0xffff0000, v159
	v_lshlrev_b32_e32 v224, 16, v160
	v_and_b32_e32 v160, 0xffff0000, v160
	v_lshlrev_b32_e32 v225, 16, v161
	v_and_b32_e32 v161, 0xffff0000, v161
	v_fmac_f32_e32 v218, v126, v222
	v_fmac_f32_e32 v154, v127, v158
	v_fmac_f32_e32 v219, v128, v223
	v_fmac_f32_e32 v155, v129, v159
	v_fmac_f32_e32 v220, v122, v224
	v_fmac_f32_e32 v156, v123, v160
	v_fmac_f32_e32 v221, v124, v225
	v_fmac_f32_e32 v157, v125, v161
	v_cvt_pk_bf16_f32 v158, v218, v154
	v_cvt_pk_bf16_f32 v159, v219, v155
	v_cvt_pk_bf16_f32 v160, v220, v156
	v_cvt_pk_bf16_f32 v161, v221, v157
	s_sub_u32 s98, s98, 0x18000
	s_subb_u32 s99, s99, 0
	global_store_dwordx4 v146, v[158:161], s[98:99] nt
	s_waitcnt vmcnt(13)
	v_lshlrev_b32_e32 v218, 16, v162
	v_and_b32_e32 v162, 0xffff0000, v162
	v_lshlrev_b32_e32 v219, 16, v163
	v_and_b32_e32 v163, 0xffff0000, v163
	v_lshlrev_b32_e32 v220, 16, v164
	v_and_b32_e32 v164, 0xffff0000, v164
	v_lshlrev_b32_e32 v221, 16, v165
	v_and_b32_e32 v165, 0xffff0000, v165
	v_lshlrev_b32_e32 v222, 16, v166
	v_and_b32_e32 v166, 0xffff0000, v166
	v_lshlrev_b32_e32 v223, 16, v167
	v_and_b32_e32 v167, 0xffff0000, v167
	v_lshlrev_b32_e32 v224, 16, v168
	v_and_b32_e32 v168, 0xffff0000, v168
	v_lshlrev_b32_e32 v225, 16, v169
	v_and_b32_e32 v169, 0xffff0000, v169
	v_fmac_f32_e32 v218, v118, v222
	v_fmac_f32_e32 v162, v119, v166
	v_fmac_f32_e32 v219, v120, v223
	v_fmac_f32_e32 v163, v121, v167
	v_fmac_f32_e32 v220, v114, v224
	v_fmac_f32_e32 v164, v115, v168
	v_fmac_f32_e32 v221, v116, v225
	v_fmac_f32_e32 v165, v117, v169
	v_cvt_pk_bf16_f32 v166, v218, v162
	v_cvt_pk_bf16_f32 v167, v219, v163
	v_cvt_pk_bf16_f32 v168, v220, v164
	v_cvt_pk_bf16_f32 v169, v221, v165
	global_store_dwordx4 v146, v[166:169], s[98:99] offset:256 nt
	s_waitcnt vmcnt(12)
	v_lshlrev_b32_e32 v218, 16, v170
	v_and_b32_e32 v170, 0xffff0000, v170
	v_lshlrev_b32_e32 v219, 16, v171
	v_and_b32_e32 v171, 0xffff0000, v171
	v_lshlrev_b32_e32 v220, 16, v172
	v_and_b32_e32 v172, 0xffff0000, v172
	v_lshlrev_b32_e32 v221, 16, v173
	v_and_b32_e32 v173, 0xffff0000, v173
	v_lshlrev_b32_e32 v222, 16, v174
	v_and_b32_e32 v174, 0xffff0000, v174
	v_lshlrev_b32_e32 v223, 16, v175
	v_and_b32_e32 v175, 0xffff0000, v175
	v_lshlrev_b32_e32 v224, 16, v176
	v_and_b32_e32 v176, 0xffff0000, v176
	v_lshlrev_b32_e32 v225, 16, v177
	v_and_b32_e32 v177, 0xffff0000, v177
	v_fmac_f32_e32 v218, v110, v222
	v_fmac_f32_e32 v170, v111, v174
	v_fmac_f32_e32 v219, v112, v223
	v_fmac_f32_e32 v171, v113, v175
	v_fmac_f32_e32 v220, v106, v224
	v_fmac_f32_e32 v172, v107, v176
	v_fmac_f32_e32 v221, v108, v225
	v_fmac_f32_e32 v173, v109, v177
	v_cvt_pk_bf16_f32 v174, v218, v170
	v_cvt_pk_bf16_f32 v175, v219, v171
	v_cvt_pk_bf16_f32 v176, v220, v172
	v_cvt_pk_bf16_f32 v177, v221, v173
	s_add_u32 s98, s98, 0x8000
	s_addc_u32 s99, s99, 0
	global_store_dwordx4 v146, v[174:177], s[98:99] nt
	s_waitcnt vmcnt(11)
	v_lshlrev_b32_e32 v218, 16, v178
	v_and_b32_e32 v178, 0xffff0000, v178
	v_lshlrev_b32_e32 v219, 16, v179
	v_and_b32_e32 v179, 0xffff0000, v179
	v_lshlrev_b32_e32 v220, 16, v180
	v_and_b32_e32 v180, 0xffff0000, v180
	v_lshlrev_b32_e32 v221, 16, v181
	v_and_b32_e32 v181, 0xffff0000, v181
	v_lshlrev_b32_e32 v222, 16, v182
	v_and_b32_e32 v182, 0xffff0000, v182
	v_lshlrev_b32_e32 v223, 16, v183
	v_and_b32_e32 v183, 0xffff0000, v183
	v_lshlrev_b32_e32 v224, 16, v184
	v_and_b32_e32 v184, 0xffff0000, v184
	v_lshlrev_b32_e32 v225, 16, v185
	v_and_b32_e32 v185, 0xffff0000, v185
	v_fmac_f32_e32 v218, v102, v222
	v_fmac_f32_e32 v178, v103, v182
	v_fmac_f32_e32 v219, v104, v223
	v_fmac_f32_e32 v179, v105, v183
	v_fmac_f32_e32 v220, v98, v224
	v_fmac_f32_e32 v180, v99, v184
	v_fmac_f32_e32 v221, v100, v225
	v_fmac_f32_e32 v181, v101, v185
	v_cvt_pk_bf16_f32 v182, v218, v178
	v_cvt_pk_bf16_f32 v183, v219, v179
	v_cvt_pk_bf16_f32 v184, v220, v180
	v_cvt_pk_bf16_f32 v185, v221, v181
	global_store_dwordx4 v146, v[182:185], s[98:99] offset:256 nt
	s_waitcnt vmcnt(10)
	v_lshlrev_b32_e32 v218, 16, v186
	v_and_b32_e32 v186, 0xffff0000, v186
	v_lshlrev_b32_e32 v219, 16, v187
	v_and_b32_e32 v187, 0xffff0000, v187
	v_lshlrev_b32_e32 v220, 16, v188
	v_and_b32_e32 v188, 0xffff0000, v188
	v_lshlrev_b32_e32 v221, 16, v189
	v_and_b32_e32 v189, 0xffff0000, v189
	v_lshlrev_b32_e32 v222, 16, v190
	v_and_b32_e32 v190, 0xffff0000, v190
	v_lshlrev_b32_e32 v223, 16, v191
	v_and_b32_e32 v191, 0xffff0000, v191
	v_lshlrev_b32_e32 v224, 16, v192
	v_and_b32_e32 v192, 0xffff0000, v192
	v_lshlrev_b32_e32 v225, 16, v193
	v_and_b32_e32 v193, 0xffff0000, v193
	v_fmac_f32_e32 v218, v94, v222
	v_fmac_f32_e32 v186, v95, v190
	v_fmac_f32_e32 v219, v96, v223
	v_fmac_f32_e32 v187, v97, v191
	v_fmac_f32_e32 v220, v90, v224
	v_fmac_f32_e32 v188, v91, v192
	v_fmac_f32_e32 v221, v92, v225
	v_fmac_f32_e32 v189, v93, v193
	v_cvt_pk_bf16_f32 v190, v218, v186
	v_cvt_pk_bf16_f32 v191, v219, v187
	v_cvt_pk_bf16_f32 v192, v220, v188
	v_cvt_pk_bf16_f32 v193, v221, v189
	s_add_u32 s98, s98, 0x8000
	s_addc_u32 s99, s99, 0
	global_store_dwordx4 v146, v[190:193], s[98:99] nt
	s_waitcnt vmcnt(9)
	v_lshlrev_b32_e32 v218, 16, v194
	v_and_b32_e32 v194, 0xffff0000, v194
	v_lshlrev_b32_e32 v219, 16, v195
	v_and_b32_e32 v195, 0xffff0000, v195
	v_lshlrev_b32_e32 v220, 16, v196
	v_and_b32_e32 v196, 0xffff0000, v196
	v_lshlrev_b32_e32 v221, 16, v197
	v_and_b32_e32 v197, 0xffff0000, v197
	v_lshlrev_b32_e32 v222, 16, v198
	v_and_b32_e32 v198, 0xffff0000, v198
	v_lshlrev_b32_e32 v223, 16, v199
	v_and_b32_e32 v199, 0xffff0000, v199
	v_lshlrev_b32_e32 v224, 16, v200
	v_and_b32_e32 v200, 0xffff0000, v200
	v_lshlrev_b32_e32 v225, 16, v201
	v_and_b32_e32 v201, 0xffff0000, v201
	v_fmac_f32_e32 v218, v86, v222
	v_fmac_f32_e32 v194, v87, v198
	v_fmac_f32_e32 v219, v88, v223
	v_fmac_f32_e32 v195, v89, v199
	v_fmac_f32_e32 v220, v82, v224
	v_fmac_f32_e32 v196, v83, v200
	v_fmac_f32_e32 v221, v84, v225
	v_fmac_f32_e32 v197, v85, v201
	v_cvt_pk_bf16_f32 v198, v218, v194
	v_cvt_pk_bf16_f32 v199, v219, v195
	v_cvt_pk_bf16_f32 v200, v220, v196
	v_cvt_pk_bf16_f32 v201, v221, v197
	global_store_dwordx4 v146, v[198:201], s[98:99] offset:256 nt
	s_waitcnt vmcnt(8)
	v_lshlrev_b32_e32 v218, 16, v202
	v_and_b32_e32 v202, 0xffff0000, v202
	v_lshlrev_b32_e32 v219, 16, v203
	v_and_b32_e32 v203, 0xffff0000, v203
	v_lshlrev_b32_e32 v220, 16, v204
	v_and_b32_e32 v204, 0xffff0000, v204
	v_lshlrev_b32_e32 v221, 16, v205
	v_and_b32_e32 v205, 0xffff0000, v205
	v_lshlrev_b32_e32 v222, 16, v206
	v_and_b32_e32 v206, 0xffff0000, v206
	v_lshlrev_b32_e32 v223, 16, v207
	v_and_b32_e32 v207, 0xffff0000, v207
	v_lshlrev_b32_e32 v224, 16, v208
	v_and_b32_e32 v208, 0xffff0000, v208
	v_lshlrev_b32_e32 v225, 16, v209
	v_and_b32_e32 v209, 0xffff0000, v209
	v_fmac_f32_e32 v218, v78, v222
	v_fmac_f32_e32 v202, v79, v206
	v_fmac_f32_e32 v219, v80, v223
	v_fmac_f32_e32 v203, v81, v207
	v_fmac_f32_e32 v220, v74, v224
	v_fmac_f32_e32 v204, v75, v208
	v_fmac_f32_e32 v221, v76, v225
	v_fmac_f32_e32 v205, v77, v209
	v_cvt_pk_bf16_f32 v206, v218, v202
	v_cvt_pk_bf16_f32 v207, v219, v203
	v_cvt_pk_bf16_f32 v208, v220, v204
	v_cvt_pk_bf16_f32 v209, v221, v205
	s_add_u32 s98, s98, 0x8000
	s_addc_u32 s99, s99, 0
	global_store_dwordx4 v146, v[206:209], s[98:99] nt
	s_waitcnt vmcnt(7)
	v_lshlrev_b32_e32 v218, 16, v210
	v_and_b32_e32 v210, 0xffff0000, v210
	v_lshlrev_b32_e32 v219, 16, v211
	v_and_b32_e32 v211, 0xffff0000, v211
	v_lshlrev_b32_e32 v220, 16, v212
	v_and_b32_e32 v212, 0xffff0000, v212
	v_lshlrev_b32_e32 v221, 16, v213
	v_and_b32_e32 v213, 0xffff0000, v213
	v_lshlrev_b32_e32 v222, 16, v214
	v_and_b32_e32 v214, 0xffff0000, v214
	v_lshlrev_b32_e32 v223, 16, v215
	v_and_b32_e32 v215, 0xffff0000, v215
	v_lshlrev_b32_e32 v224, 16, v216
	v_and_b32_e32 v216, 0xffff0000, v216
	v_lshlrev_b32_e32 v225, 16, v217
	v_and_b32_e32 v217, 0xffff0000, v217
	v_fmac_f32_e32 v218, v70, v222
	v_fmac_f32_e32 v210, v71, v214
	v_fmac_f32_e32 v219, v72, v223
	v_fmac_f32_e32 v211, v73, v215
	v_fmac_f32_e32 v220, v66, v224
	v_fmac_f32_e32 v212, v67, v216
	v_fmac_f32_e32 v221, v68, v225
	v_fmac_f32_e32 v213, v69, v217
	v_cvt_pk_bf16_f32 v214, v218, v210
	v_cvt_pk_bf16_f32 v215, v219, v211
	v_cvt_pk_bf16_f32 v216, v220, v212
	v_cvt_pk_bf16_f32 v217, v221, v213
	global_store_dwordx4 v146, v[214:217], s[98:99] offset:256 nt
	s_add_u32 s98, s98, 0x28000
	s_addc_u32 s99, s99, 0
	global_load_dwordx4 v[154:157], v146, s[98:99]
	global_load_dwordx4 v[158:161], v147, s[98:99]
	global_load_dwordx4 v[162:165], v146, s[98:99] offset:256
	global_load_dwordx4 v[166:169], v147, s[98:99] offset:256
	s_add_u32 s98, s98, 0x8000
	s_addc_u32 s99, s99, 0
	global_load_dwordx4 v[170:173], v146, s[98:99]
	global_load_dwordx4 v[174:177], v147, s[98:99]
	global_load_dwordx4 v[178:181], v146, s[98:99] offset:256
	global_load_dwordx4 v[182:185], v147, s[98:99] offset:256
	s_add_u32 s98, s98, 0x8000
	s_addc_u32 s99, s99, 0
	global_load_dwordx4 v[186:189], v146, s[98:99]
	global_load_dwordx4 v[190:193], v147, s[98:99]
	global_load_dwordx4 v[194:197], v146, s[98:99] offset:256
	global_load_dwordx4 v[198:201], v147, s[98:99] offset:256
	s_add_u32 s98, s98, 0x8000
	s_addc_u32 s99, s99, 0
	global_load_dwordx4 v[202:205], v146, s[98:99]
	global_load_dwordx4 v[206:209], v147, s[98:99]
	global_load_dwordx4 v[210:213], v146, s[98:99] offset:256
	global_load_dwordx4 v[214:217], v147, s[98:99] offset:256
	s_waitcnt vmcnt(14)
	v_lshlrev_b32_e32 v218, 16, v154
	v_and_b32_e32 v154, 0xffff0000, v154
	v_lshlrev_b32_e32 v219, 16, v155
	v_and_b32_e32 v155, 0xffff0000, v155
	v_lshlrev_b32_e32 v220, 16, v156
	v_and_b32_e32 v156, 0xffff0000, v156
	v_lshlrev_b32_e32 v221, 16, v157
	v_and_b32_e32 v157, 0xffff0000, v157
	v_lshlrev_b32_e32 v222, 16, v158
	v_and_b32_e32 v158, 0xffff0000, v158
	v_lshlrev_b32_e32 v223, 16, v159
	v_and_b32_e32 v159, 0xffff0000, v159
	v_lshlrev_b32_e32 v224, 16, v160
	v_and_b32_e32 v160, 0xffff0000, v160
	v_lshlrev_b32_e32 v225, 16, v161
	v_and_b32_e32 v161, 0xffff0000, v161
	v_fmac_f32_e32 v218, v62, v222
	v_fmac_f32_e32 v154, v63, v158
	v_fmac_f32_e32 v219, v64, v223
	v_fmac_f32_e32 v155, v65, v159
	v_fmac_f32_e32 v220, v58, v224
	v_fmac_f32_e32 v156, v59, v160
	v_fmac_f32_e32 v221, v60, v225
	v_fmac_f32_e32 v157, v61, v161
	v_cvt_pk_bf16_f32 v158, v218, v154
	v_cvt_pk_bf16_f32 v159, v219, v155
	v_cvt_pk_bf16_f32 v160, v220, v156
	v_cvt_pk_bf16_f32 v161, v221, v157
	s_sub_u32 s98, s98, 0x18000
	s_subb_u32 s99, s99, 0
	global_store_dwordx4 v146, v[158:161], s[98:99] nt
	s_waitcnt vmcnt(13)
	v_lshlrev_b32_e32 v218, 16, v162
	v_and_b32_e32 v162, 0xffff0000, v162
	v_lshlrev_b32_e32 v219, 16, v163
	v_and_b32_e32 v163, 0xffff0000, v163
	v_lshlrev_b32_e32 v220, 16, v164
	v_and_b32_e32 v164, 0xffff0000, v164
	v_lshlrev_b32_e32 v221, 16, v165
	v_and_b32_e32 v165, 0xffff0000, v165
	v_lshlrev_b32_e32 v222, 16, v166
	v_and_b32_e32 v166, 0xffff0000, v166
	v_lshlrev_b32_e32 v223, 16, v167
	v_and_b32_e32 v167, 0xffff0000, v167
	v_lshlrev_b32_e32 v224, 16, v168
	v_and_b32_e32 v168, 0xffff0000, v168
	v_lshlrev_b32_e32 v225, 16, v169
	v_and_b32_e32 v169, 0xffff0000, v169
	v_fmac_f32_e32 v218, v54, v222
	v_fmac_f32_e32 v162, v55, v166
	v_fmac_f32_e32 v219, v56, v223
	v_fmac_f32_e32 v163, v57, v167
	v_fmac_f32_e32 v220, v50, v224
	v_fmac_f32_e32 v164, v51, v168
	v_fmac_f32_e32 v221, v52, v225
	v_fmac_f32_e32 v165, v53, v169
	v_cvt_pk_bf16_f32 v166, v218, v162
	v_cvt_pk_bf16_f32 v167, v219, v163
	v_cvt_pk_bf16_f32 v168, v220, v164
	v_cvt_pk_bf16_f32 v169, v221, v165
	global_store_dwordx4 v146, v[166:169], s[98:99] offset:256 nt
	s_waitcnt vmcnt(12)
	v_lshlrev_b32_e32 v218, 16, v170
	v_and_b32_e32 v170, 0xffff0000, v170
	v_lshlrev_b32_e32 v219, 16, v171
	v_and_b32_e32 v171, 0xffff0000, v171
	v_lshlrev_b32_e32 v220, 16, v172
	v_and_b32_e32 v172, 0xffff0000, v172
	v_lshlrev_b32_e32 v221, 16, v173
	v_and_b32_e32 v173, 0xffff0000, v173
	v_lshlrev_b32_e32 v222, 16, v174
	v_and_b32_e32 v174, 0xffff0000, v174
	v_lshlrev_b32_e32 v223, 16, v175
	v_and_b32_e32 v175, 0xffff0000, v175
	v_lshlrev_b32_e32 v224, 16, v176
	v_and_b32_e32 v176, 0xffff0000, v176
	v_lshlrev_b32_e32 v225, 16, v177
	v_and_b32_e32 v177, 0xffff0000, v177
	v_fmac_f32_e32 v218, v46, v222
	v_fmac_f32_e32 v170, v47, v174
	v_fmac_f32_e32 v219, v48, v223
	v_fmac_f32_e32 v171, v49, v175
	v_fmac_f32_e32 v220, v42, v224
	v_fmac_f32_e32 v172, v43, v176
	v_fmac_f32_e32 v221, v44, v225
	v_fmac_f32_e32 v173, v45, v177
	v_cvt_pk_bf16_f32 v174, v218, v170
	v_cvt_pk_bf16_f32 v175, v219, v171
	v_cvt_pk_bf16_f32 v176, v220, v172
	v_cvt_pk_bf16_f32 v177, v221, v173
	s_add_u32 s98, s98, 0x8000
	s_addc_u32 s99, s99, 0
	global_store_dwordx4 v146, v[174:177], s[98:99] nt
	s_waitcnt vmcnt(11)
	v_lshlrev_b32_e32 v218, 16, v178
	v_and_b32_e32 v178, 0xffff0000, v178
	v_lshlrev_b32_e32 v219, 16, v179
	v_and_b32_e32 v179, 0xffff0000, v179
	v_lshlrev_b32_e32 v220, 16, v180
	v_and_b32_e32 v180, 0xffff0000, v180
	v_lshlrev_b32_e32 v221, 16, v181
	v_and_b32_e32 v181, 0xffff0000, v181
	v_lshlrev_b32_e32 v222, 16, v182
	v_and_b32_e32 v182, 0xffff0000, v182
	v_lshlrev_b32_e32 v223, 16, v183
	v_and_b32_e32 v183, 0xffff0000, v183
	v_lshlrev_b32_e32 v224, 16, v184
	v_and_b32_e32 v184, 0xffff0000, v184
	v_lshlrev_b32_e32 v225, 16, v185
	v_and_b32_e32 v185, 0xffff0000, v185
	v_fmac_f32_e32 v218, v38, v222
	v_fmac_f32_e32 v178, v39, v182
	v_fmac_f32_e32 v219, v40, v223
	v_fmac_f32_e32 v179, v41, v183
	v_fmac_f32_e32 v220, v34, v224
	v_fmac_f32_e32 v180, v35, v184
	v_fmac_f32_e32 v221, v36, v225
	v_fmac_f32_e32 v181, v37, v185
	v_cvt_pk_bf16_f32 v182, v218, v178
	v_cvt_pk_bf16_f32 v183, v219, v179
	v_cvt_pk_bf16_f32 v184, v220, v180
	v_cvt_pk_bf16_f32 v185, v221, v181
	global_store_dwordx4 v146, v[182:185], s[98:99] offset:256 nt
	s_waitcnt vmcnt(10)
	v_lshlrev_b32_e32 v218, 16, v186
	v_and_b32_e32 v186, 0xffff0000, v186
	v_lshlrev_b32_e32 v219, 16, v187
	v_and_b32_e32 v187, 0xffff0000, v187
	v_lshlrev_b32_e32 v220, 16, v188
	v_and_b32_e32 v188, 0xffff0000, v188
	v_lshlrev_b32_e32 v221, 16, v189
	v_and_b32_e32 v189, 0xffff0000, v189
	v_lshlrev_b32_e32 v222, 16, v190
	v_and_b32_e32 v190, 0xffff0000, v190
	v_lshlrev_b32_e32 v223, 16, v191
	v_and_b32_e32 v191, 0xffff0000, v191
	v_lshlrev_b32_e32 v224, 16, v192
	v_and_b32_e32 v192, 0xffff0000, v192
	v_lshlrev_b32_e32 v225, 16, v193
	v_and_b32_e32 v193, 0xffff0000, v193
	v_fmac_f32_e32 v218, v30, v222
	v_fmac_f32_e32 v186, v31, v190
	v_fmac_f32_e32 v219, v32, v223
	v_fmac_f32_e32 v187, v33, v191
	v_fmac_f32_e32 v220, v26, v224
	v_fmac_f32_e32 v188, v27, v192
	v_fmac_f32_e32 v221, v28, v225
	v_fmac_f32_e32 v189, v29, v193
	v_cvt_pk_bf16_f32 v190, v218, v186
	v_cvt_pk_bf16_f32 v191, v219, v187
	v_cvt_pk_bf16_f32 v192, v220, v188
	v_cvt_pk_bf16_f32 v193, v221, v189
	s_add_u32 s98, s98, 0x8000
	s_addc_u32 s99, s99, 0
	global_store_dwordx4 v146, v[190:193], s[98:99] nt
	s_waitcnt vmcnt(9)
	v_lshlrev_b32_e32 v218, 16, v194
	v_and_b32_e32 v194, 0xffff0000, v194
	v_lshlrev_b32_e32 v219, 16, v195
	v_and_b32_e32 v195, 0xffff0000, v195
	v_lshlrev_b32_e32 v220, 16, v196
	v_and_b32_e32 v196, 0xffff0000, v196
	v_lshlrev_b32_e32 v221, 16, v197
	v_and_b32_e32 v197, 0xffff0000, v197
	v_lshlrev_b32_e32 v222, 16, v198
	v_and_b32_e32 v198, 0xffff0000, v198
	v_lshlrev_b32_e32 v223, 16, v199
	v_and_b32_e32 v199, 0xffff0000, v199
	v_lshlrev_b32_e32 v224, 16, v200
	v_and_b32_e32 v200, 0xffff0000, v200
	v_lshlrev_b32_e32 v225, 16, v201
	v_and_b32_e32 v201, 0xffff0000, v201
	v_fmac_f32_e32 v218, v22, v222
	v_fmac_f32_e32 v194, v23, v198
	v_fmac_f32_e32 v219, v24, v223
	v_fmac_f32_e32 v195, v25, v199
	v_fmac_f32_e32 v220, v18, v224
	v_fmac_f32_e32 v196, v19, v200
	v_fmac_f32_e32 v221, v20, v225
	v_fmac_f32_e32 v197, v21, v201
	v_cvt_pk_bf16_f32 v198, v218, v194
	v_cvt_pk_bf16_f32 v199, v219, v195
	v_cvt_pk_bf16_f32 v200, v220, v196
	v_cvt_pk_bf16_f32 v201, v221, v197
	global_store_dwordx4 v146, v[198:201], s[98:99] offset:256 nt
	s_waitcnt vmcnt(8)
	v_lshlrev_b32_e32 v218, 16, v202
	v_and_b32_e32 v202, 0xffff0000, v202
	v_lshlrev_b32_e32 v219, 16, v203
	v_and_b32_e32 v203, 0xffff0000, v203
	v_lshlrev_b32_e32 v220, 16, v204
	v_and_b32_e32 v204, 0xffff0000, v204
	v_lshlrev_b32_e32 v221, 16, v205
	v_and_b32_e32 v205, 0xffff0000, v205
	v_lshlrev_b32_e32 v222, 16, v206
	v_and_b32_e32 v206, 0xffff0000, v206
	v_lshlrev_b32_e32 v223, 16, v207
	v_and_b32_e32 v207, 0xffff0000, v207
	v_lshlrev_b32_e32 v224, 16, v208
	v_and_b32_e32 v208, 0xffff0000, v208
	v_lshlrev_b32_e32 v225, 16, v209
	v_and_b32_e32 v209, 0xffff0000, v209
	v_fmac_f32_e32 v218, v14, v222
	v_fmac_f32_e32 v202, v15, v206
	v_fmac_f32_e32 v219, v16, v223
	v_fmac_f32_e32 v203, v17, v207
	v_fmac_f32_e32 v220, v10, v224
	v_fmac_f32_e32 v204, v11, v208
	v_fmac_f32_e32 v221, v12, v225
	v_fmac_f32_e32 v205, v13, v209
	v_cvt_pk_bf16_f32 v206, v218, v202
	v_cvt_pk_bf16_f32 v207, v219, v203
	v_cvt_pk_bf16_f32 v208, v220, v204
	v_cvt_pk_bf16_f32 v209, v221, v205
	s_add_u32 s98, s98, 0x8000
	s_addc_u32 s99, s99, 0
	global_store_dwordx4 v146, v[206:209], s[98:99] nt
	s_waitcnt vmcnt(7)
	v_lshlrev_b32_e32 v218, 16, v210
	v_and_b32_e32 v210, 0xffff0000, v210
	v_lshlrev_b32_e32 v219, 16, v211
	v_and_b32_e32 v211, 0xffff0000, v211
	v_lshlrev_b32_e32 v220, 16, v212
	v_and_b32_e32 v212, 0xffff0000, v212
	v_lshlrev_b32_e32 v221, 16, v213
	v_and_b32_e32 v213, 0xffff0000, v213
	v_lshlrev_b32_e32 v222, 16, v214
	v_and_b32_e32 v214, 0xffff0000, v214
	v_lshlrev_b32_e32 v223, 16, v215
	v_and_b32_e32 v215, 0xffff0000, v215
	v_lshlrev_b32_e32 v224, 16, v216
	v_and_b32_e32 v216, 0xffff0000, v216
	v_lshlrev_b32_e32 v225, 16, v217
	v_and_b32_e32 v217, 0xffff0000, v217
	v_fmac_f32_e32 v218, v6, v222
	v_fmac_f32_e32 v210, v7, v214
	v_fmac_f32_e32 v219, v8, v223
	v_fmac_f32_e32 v211, v9, v215
	v_fmac_f32_e32 v220, v2, v224
	v_fmac_f32_e32 v212, v3, v216
	v_fmac_f32_e32 v221, v4, v225
	v_fmac_f32_e32 v213, v5, v217
	v_cvt_pk_bf16_f32 v214, v218, v210
	v_cvt_pk_bf16_f32 v215, v219, v211
	v_cvt_pk_bf16_f32 v216, v220, v212
	v_cvt_pk_bf16_f32 v217, v221, v213
	global_store_dwordx4 v146, v[214:217], s[98:99] offset:256 nt
	s_andn2_b64 vcc, exec, s[0:1]
	s_mov_b64 s[0:1], -1
	s_mov_b32 s100, 1
	s_cbranch_vccnz .LBB0_576
	s_andn2_b64 vcc, exec, s[8:9]
	s_cbranch_vccnz .LBB0_575
	s_barrier
	s_branch .LBB0_575

.Lrwp4_exit:
.LBB0_665:
	v_mov_b32_e32 v236, v229
	v_mov_b32_e32 v237, v228
	v_mov_b32_e32 v238, v0
	s_ashr_i32 s0, s64, 3
	s_lshl_b32 s10, s64, 8
	s_lshl_b32 s55, s62, 8
	v_lshlrev_b32_e32 v239, 2, v236
	s_mul_hi_i32 s1, s0, 0x1800
	s_mulk_i32 s0, 0x1800
	s_add_i32 s31, s10, s85
	v_add_u32_e32 v130, s55, v239
	s_lshl_b64 s[66:67], s[0:1], 2
	s_add_u32 s0, s81, s66
	v_ashrrev_i32_e32 v131, 31, v130
	v_add_u32_e32 v224, s31, v237
	s_addc_u32 s1, s82, s67
	v_lshlrev_b64 v[130:131], 2, v[130:131]
	v_ashrrev_i32_e32 v225, 31, v224
	v_lshl_add_u64 v[132:133], s[0:1], 0, v[130:131]
	v_lshl_add_u64 v[226:227], s[36:37], 0, v[130:131]
	v_lshlrev_b64 v[130:131], 12, v[224:225]
	v_lshl_add_u64 v[132:133], v[132:133], 0, s[42:43]
	v_lshl_add_u64 v[130:131], v[226:227], 0, v[130:131]
	v_lshl_add_u64 v[146:147], v[130:131], 0, s[42:43]
	global_load_dwordx4 v[142:145], v[132:133], off
	global_load_dwordx4 v[138:141], v[132:133], off offset:64
	global_load_dwordx4 v[208:211], v[146:147], off
	global_load_dwordx4 v[216:219], v[146:147], off offset:64
	global_load_dwordx4 v[134:137], v[132:133], off offset:128
	s_nop 0
	global_load_dwordx4 v[130:133], v[132:133], off offset:192
	s_nop 0
	global_load_dwordx4 v[240:243], v[146:147], off offset:128
	global_load_dwordx4 v[244:247], v[146:147], off offset:192
	s_mov_b64 s[0:1], 0x10000
	v_lshl_add_u64 v[148:149], v[146:147], 0, s[0:1]
	s_mov_b32 s0, 0x10000
	v_add_co_u32_e32 v150, vcc, s0, v146
	s_mov_b64 s[0:1], 0x20000
	s_nop 0
	v_addc_co_u32_e32 v151, vcc, 0, v147, vcc
	global_load_dwordx4 v[186:189], v[148:149], off offset:64
	global_load_dwordx4 v[182:185], v[148:149], off offset:128
	global_load_dwordx4 v[190:193], v[150:151], off
	global_load_dwordx4 v[178:181], v[148:149], off offset:192
	v_lshl_add_u64 v[148:149], v[146:147], 0, s[0:1]
	s_mov_b32 s0, 0x20000
	v_add_co_u32_e32 v150, vcc, s0, v146
	s_mov_b64 s[0:1], 0x30000
	s_nop 0
	v_addc_co_u32_e32 v151, vcc, 0, v147, vcc
	global_load_dwordx4 v[170:173], v[148:149], off offset:64
	global_load_dwordx4 v[166:169], v[148:149], off offset:128
	global_load_dwordx4 v[174:177], v[150:151], off
	global_load_dwordx4 v[162:165], v[148:149], off offset:192
	v_lshl_add_u64 v[148:149], v[146:147], 0, s[0:1]
	s_mov_b32 s0, 0x30000
	v_add_co_u32_e32 v146, vcc, s0, v146
	v_add_u32_e32 v248, s85, v237
	s_nop 0
	v_addc_co_u32_e32 v147, vcc, 0, v147, vcc
	global_load_dwordx4 v[154:157], v[148:149], off offset:64
	global_load_dwordx4 v[150:153], v[148:149], off offset:128
	global_load_dwordx4 v[158:161], v[146:147], off
	s_nop 0
	global_load_dwordx4 v[146:149], v[148:149], off offset:192
	v_readfirstlane_b32 s57, v238
	v_cmp_eq_u32_e64 s[0:1], 0, v236
	s_cmp_lg_u64 s[52:53], 0
	s_cbranch_scc0 .Lp4_nobar
	s_barrier
.Lp4_nobar:
	s_waitcnt vmcnt(0)
	v_pk_fma_f32 v[214:215], v[128:129], v[144:145], v[210:211]
	v_pk_fma_f32 v[222:223], v[126:127], v[142:143], v[208:209]
	v_pk_fma_f32 v[212:213], v[124:125], v[140:141], v[218:219]
	v_pk_fma_f32 v[220:221], v[122:123], v[138:139], v[216:217]
	v_pk_fma_f32 v[210:211], v[120:121], v[136:137], v[242:243]
	v_pk_fma_f32 v[218:219], v[118:119], v[134:135], v[240:241]
	v_pk_fma_f32 v[208:209], v[116:117], v[132:133], v[246:247]
	v_pk_fma_f32 v[216:217], v[114:115], v[130:131], v[244:245]
	v_mul_f32_e32 v114, v223, v223
	v_mul_f32_e32 v115, v215, v215
	v_mul_f32_e32 v116, v221, v221
	v_mul_f32_e32 v117, v213, v213
	v_mul_f32_e32 v118, v219, v219
	v_mul_f32_e32 v119, v211, v211
	v_fmac_f32_e32 v114, v222, v222
	v_fmac_f32_e32 v115, v214, v214
	v_fmac_f32_e32 v116, v220, v220
	v_fmac_f32_e32 v117, v212, v212
	v_mul_f32_e32 v120, v217, v217
	v_mul_f32_e32 v121, v209, v209
	v_fmac_f32_e32 v118, v218, v218
	v_fmac_f32_e32 v119, v210, v210
	v_add_f32_e32 v114, v114, v115
	v_add_f32_e32 v115, v116, v117
	v_fmac_f32_e32 v120, v216, v216
	v_fmac_f32_e32 v121, v208, v208
	v_add_f32_e32 v116, v118, v119
	v_add_f32_e32 v114, v114, v115
	v_add_f32_e32 v117, v120, v121
	v_add_f32_e32 v114, v114, v116
	v_add_f32_e32 v114, v114, v117
	v_mov_b32_e32 v115, v114
	s_nop 1
	v_permlane16_swap_b32_e32 v114, v115
	v_add_f32_e32 v114, v114, v115
	v_mov_b32_e32 v115, v114
	s_nop 1
	v_permlane32_swap_b32_e32 v114, v115
	v_lshl_add_u32 v240, v248, 4, s92
	s_and_saveexec_b64 s[8:9], s[0:1]
	v_add_f32_e32 v114, v114, v115
	ds_write_b32 v240, v114
	s_or_b64 exec, exec, s[8:9]
	v_pk_fma_f32 v[192:193], v[112:113], v[144:145], v[192:193]
	v_pk_fma_f32 v[190:191], v[110:111], v[142:143], v[190:191]
	v_pk_fma_f32 v[188:189], v[108:109], v[140:141], v[188:189]
	v_pk_fma_f32 v[186:187], v[106:107], v[138:139], v[186:187]
	v_mul_f32_e32 v110, v191, v191
	v_mul_f32_e32 v111, v193, v193
	v_mul_f32_e32 v106, v187, v187
	v_mul_f32_e32 v107, v189, v189
	v_pk_fma_f32 v[184:185], v[104:105], v[136:137], v[184:185]
	v_pk_fma_f32 v[182:183], v[102:103], v[134:135], v[182:183]
	v_fmac_f32_e32 v110, v190, v190
	v_fmac_f32_e32 v111, v192, v192
	v_fmac_f32_e32 v106, v186, v186
	v_fmac_f32_e32 v107, v188, v188
	v_mul_f32_e32 v102, v183, v183
	v_mul_f32_e32 v103, v185, v185
	v_pk_fma_f32 v[180:181], v[100:101], v[132:133], v[180:181]
	v_pk_fma_f32 v[178:179], v[98:99], v[130:131], v[178:179]
	v_add_f32_e32 v110, v110, v111
	v_add_f32_e32 v106, v106, v107
	v_fmac_f32_e32 v102, v182, v182
	v_fmac_f32_e32 v103, v184, v184
	v_mul_f32_e32 v98, v179, v179
	v_mul_f32_e32 v99, v181, v181
	v_add_f32_e32 v106, v110, v106
	v_add_f32_e32 v102, v102, v103
	v_fmac_f32_e32 v98, v178, v178
	v_fmac_f32_e32 v99, v180, v180
	v_add_f32_e32 v102, v106, v102
	v_add_f32_e32 v98, v98, v99
	v_add_f32_e32 v98, v102, v98
	v_mov_b32_e32 v99, v98
	s_nop 1
	v_permlane16_swap_b32_e32 v98, v99
	v_add_f32_e32 v98, v98, v99
	v_mov_b32_e32 v99, v98
	s_nop 1
	v_permlane32_swap_b32_e32 v98, v99
	s_and_saveexec_b64 s[8:9], s[0:1]
	v_add_f32_e32 v98, v98, v99
	ds_write_b32 v240, v98 offset:256
	s_or_b64 exec, exec, s[8:9]
	v_pk_fma_f32 v[176:177], v[96:97], v[144:145], v[176:177]
	v_pk_fma_f32 v[174:175], v[94:95], v[142:143], v[174:175]
	v_pk_fma_f32 v[172:173], v[92:93], v[140:141], v[172:173]
	v_pk_fma_f32 v[170:171], v[90:91], v[138:139], v[170:171]
	v_mul_f32_e32 v94, v175, v175
	v_mul_f32_e32 v95, v177, v177
	v_mul_f32_e32 v90, v171, v171
	v_mul_f32_e32 v91, v173, v173
	v_pk_fma_f32 v[168:169], v[88:89], v[136:137], v[168:169]
	v_pk_fma_f32 v[166:167], v[86:87], v[134:135], v[166:167]
	v_fmac_f32_e32 v94, v174, v174
	v_fmac_f32_e32 v95, v176, v176
	v_fmac_f32_e32 v90, v170, v170
	v_fmac_f32_e32 v91, v172, v172
	v_mul_f32_e32 v86, v167, v167
	v_mul_f32_e32 v87, v169, v169
	v_pk_fma_f32 v[164:165], v[84:85], v[132:133], v[164:165]
	v_pk_fma_f32 v[162:163], v[82:83], v[130:131], v[162:163]
	v_add_f32_e32 v94, v94, v95
	v_add_f32_e32 v90, v90, v91
	v_fmac_f32_e32 v86, v166, v166
	v_fmac_f32_e32 v87, v168, v168
	v_mul_f32_e32 v82, v163, v163
	v_mul_f32_e32 v83, v165, v165
	v_add_f32_e32 v90, v94, v90
	v_add_f32_e32 v86, v86, v87
	v_fmac_f32_e32 v82, v162, v162
	v_fmac_f32_e32 v83, v164, v164
	v_add_f32_e32 v86, v90, v86
	v_add_f32_e32 v82, v82, v83
	v_add_f32_e32 v82, v86, v82
	v_mov_b32_e32 v83, v82
	s_nop 1
	v_permlane16_swap_b32_e32 v82, v83
	v_add_f32_e32 v82, v82, v83
	v_mov_b32_e32 v83, v82
	s_nop 1
	v_permlane32_swap_b32_e32 v82, v83
	s_and_saveexec_b64 s[8:9], s[0:1]
	v_add_f32_e32 v82, v82, v83
	ds_write_b32 v240, v82 offset:512
	s_or_b64 exec, exec, s[8:9]
	v_pk_fma_f32 v[120:121], v[80:81], v[144:145], v[160:161]
	v_pk_fma_f32 v[128:129], v[78:79], v[142:143], v[158:159]
	v_pk_fma_f32 v[118:119], v[76:77], v[140:141], v[156:157]
	v_pk_fma_f32 v[126:127], v[74:75], v[138:139], v[154:155]
	v_mul_f32_e32 v78, v129, v129
	v_mul_f32_e32 v79, v121, v121
	v_mul_f32_e32 v74, v127, v127
	v_mul_f32_e32 v75, v119, v119
	v_pk_fma_f32 v[116:117], v[72:73], v[136:137], v[152:153]
	v_pk_fma_f32 v[124:125], v[70:71], v[134:135], v[150:151]
	v_fmac_f32_e32 v78, v128, v128
	v_fmac_f32_e32 v79, v120, v120
	v_fmac_f32_e32 v74, v126, v126
	v_fmac_f32_e32 v75, v118, v118
	v_mul_f32_e32 v70, v125, v125
	v_mul_f32_e32 v71, v117, v117
	v_pk_fma_f32 v[114:115], v[68:69], v[132:133], v[148:149]
	v_pk_fma_f32 v[122:123], v[66:67], v[130:131], v[146:147]
	v_add_f32_e32 v78, v78, v79
	v_add_f32_e32 v74, v74, v75
	v_fmac_f32_e32 v70, v124, v124
	v_fmac_f32_e32 v71, v116, v116
	v_mul_f32_e32 v66, v123, v123
	v_mul_f32_e32 v67, v115, v115
	v_add_f32_e32 v74, v78, v74
	v_add_f32_e32 v70, v70, v71
	v_fmac_f32_e32 v66, v122, v122
	v_fmac_f32_e32 v67, v114, v114
	v_add_f32_e32 v70, v74, v70
	v_add_f32_e32 v66, v66, v67
	v_add_f32_e32 v66, v70, v66
	v_mov_b32_e32 v67, v66
	s_nop 1
	v_permlane16_swap_b32_e32 v66, v67
	v_add_f32_e32 v66, v66, v67
	v_mov_b32_e32 v67, v66
	s_nop 1
	v_permlane32_swap_b32_e32 v66, v67
	s_and_saveexec_b64 s[8:9], s[0:1]
	v_add_f32_e32 v66, v66, v67
	ds_write_b32 v240, v66 offset:768
	s_or_b64 exec, exec, s[8:9]
	v_lshlrev_b64 v[66:67], 12, v[224:225]
	v_lshl_add_u64 v[66:67], v[226:227], 0, v[66:67]
	v_lshl_add_u64 v[66:67], v[66:67], 0, s[42:43]
	s_mov_b64 s[6:7], 0x80000
	v_lshl_add_u64 v[68:69], v[66:67], 0, s[6:7]
	v_add_co_u32_e32 v70, vcc, 0x80000, v66
	global_load_dwordx4 v[146:149], v[68:69], off offset:64
	global_load_dwordx4 v[150:153], v[68:69], off offset:128
	v_addc_co_u32_e32 v71, vcc, 0, v67, vcc
	global_load_dwordx4 v[154:157], v[70:71], off
	global_load_dwordx4 v[158:161], v[68:69], off offset:192
	s_mov_b64 s[6:7], 0x90000
	v_add_co_u32_e32 v70, vcc, 0x90000, v66
	v_lshl_add_u64 v[68:69], v[66:67], 0, s[6:7]
	s_nop 0
	v_addc_co_u32_e32 v71, vcc, 0, v67, vcc
	global_load_dwordx4 v[106:109], v[68:69], off offset:64
	global_load_dwordx4 v[102:105], v[68:69], off offset:128
	global_load_dwordx4 v[110:113], v[70:71], off
	global_load_dwordx4 v[98:101], v[68:69], off offset:192
	s_mov_b64 s[6:7], 0xa0000
	v_add_co_u32_e32 v70, vcc, 0xa0000, v66
	v_lshl_add_u64 v[68:69], v[66:67], 0, s[6:7]
	s_nop 0
	v_addc_co_u32_e32 v71, vcc, 0, v67, vcc
	s_mov_b64 s[6:7], 0xb0000
	global_load_dwordx4 v[90:93], v[68:69], off offset:64
	global_load_dwordx4 v[86:89], v[68:69], off offset:128
	global_load_dwordx4 v[94:97], v[70:71], off
	global_load_dwordx4 v[82:85], v[68:69], off offset:192
	v_lshl_add_u64 v[68:69], v[66:67], 0, s[6:7]
	v_add_co_u32_e32 v66, vcc, 0xb0000, v66
	s_waitcnt vmcnt(11)
	v_pk_fma_f32 v[64:65], v[64:65], v[140:141], v[148:149]
	v_addc_co_u32_e32 v67, vcc, 0, v67, vcc
	global_load_dwordx4 v[74:77], v[68:69], off offset:64
	global_load_dwordx4 v[70:73], v[68:69], off offset:128
	global_load_dwordx4 v[78:81], v[66:67], off
	s_nop 0
	global_load_dwordx4 v[66:69], v[68:69], off offset:192
	v_pk_fma_f32 v[62:63], v[62:63], v[138:139], v[146:147]
	s_waitcnt vmcnt(14)
	v_pk_fma_f32 v[54:55], v[54:55], v[134:135], v[150:151]
	s_waitcnt vmcnt(13)
	v_pk_fma_f32 v[148:149], v[60:61], v[144:145], v[156:157]
	v_pk_fma_f32 v[150:151], v[58:59], v[142:143], v[154:155]
	v_pk_fma_f32 v[56:57], v[56:57], v[136:137], v[152:153]
	v_mul_f32_e32 v58, v63, v63
	v_mul_f32_e32 v59, v65, v65
	s_waitcnt vmcnt(12)
	v_pk_fma_f32 v[146:147], v[50:51], v[130:131], v[158:159]
	v_mul_f32_e32 v50, v151, v151
	v_mul_f32_e32 v51, v149, v149
	v_mul_f32_e32 v60, v55, v55
	v_mul_f32_e32 v61, v57, v57
	v_pk_fma_f32 v[52:53], v[52:53], v[132:133], v[160:161]
	v_fmac_f32_e32 v58, v62, v62
	v_fmac_f32_e32 v59, v64, v64
	v_fmac_f32_e32 v50, v150, v150
	v_fmac_f32_e32 v51, v148, v148
	v_fmac_f32_e32 v60, v54, v54
	v_fmac_f32_e32 v61, v56, v56
	v_mul_f32_e32 v152, v147, v147
	v_mul_f32_e32 v153, v53, v53
	v_add_f32_e32 v58, v58, v59
	v_add_f32_e32 v50, v50, v51
	v_add_f32_e32 v59, v60, v61
	v_fmac_f32_e32 v152, v146, v146
	v_fmac_f32_e32 v153, v52, v52
	v_add_f32_e32 v50, v50, v58
	v_add_f32_e32 v51, v152, v153
	v_add_f32_e32 v50, v50, v59
	v_add_f32_e32 v50, v50, v51
	v_mov_b32_e32 v51, v50
	s_nop 1
	v_permlane16_swap_b32_e32 v50, v51
	v_add_f32_e32 v50, v50, v51
	v_mov_b32_e32 v51, v50
	s_nop 1
	v_permlane32_swap_b32_e32 v50, v51
	s_and_saveexec_b64 s[8:9], s[0:1]
	v_add_f32_e32 v50, v50, v51
	ds_write_b32 v240, v50 offset:2048
	s_or_b64 exec, exec, s[8:9]
	s_waitcnt vmcnt(9)
	v_pk_fma_f32 v[112:113], v[48:49], v[144:145], v[112:113]
	v_pk_fma_f32 v[110:111], v[46:47], v[142:143], v[110:111]
	v_pk_fma_f32 v[60:61], v[44:45], v[140:141], v[108:109]
	v_pk_fma_f32 v[106:107], v[42:43], v[138:139], v[106:107]
	v_mul_f32_e32 v46, v111, v111
	v_mul_f32_e32 v47, v113, v113
	v_mul_f32_e32 v42, v107, v107
	v_mul_f32_e32 v43, v61, v61
	v_pk_fma_f32 v[58:59], v[40:41], v[136:137], v[104:105]
	v_pk_fma_f32 v[102:103], v[38:39], v[134:135], v[102:103]
	v_fmac_f32_e32 v46, v110, v110
	v_fmac_f32_e32 v47, v112, v112
	v_fmac_f32_e32 v42, v106, v106
	v_fmac_f32_e32 v43, v60, v60
	v_mul_f32_e32 v38, v103, v103
	v_mul_f32_e32 v39, v59, v59
	s_waitcnt vmcnt(8)
	v_pk_fma_f32 v[50:51], v[36:37], v[132:133], v[100:101]
	v_pk_fma_f32 v[98:99], v[34:35], v[130:131], v[98:99]
	v_add_f32_e32 v46, v46, v47
	v_add_f32_e32 v42, v42, v43
	v_fmac_f32_e32 v38, v102, v102
	v_fmac_f32_e32 v39, v58, v58
	v_mul_f32_e32 v34, v99, v99
	v_mul_f32_e32 v35, v51, v51
	v_add_f32_e32 v42, v46, v42
	v_add_f32_e32 v38, v38, v39
	v_fmac_f32_e32 v34, v98, v98
	v_fmac_f32_e32 v35, v50, v50
	v_add_f32_e32 v38, v42, v38
	v_add_f32_e32 v34, v34, v35
	v_add_f32_e32 v34, v38, v34
	v_mov_b32_e32 v35, v34
	s_nop 1
	v_permlane16_swap_b32_e32 v34, v35
	v_add_f32_e32 v34, v34, v35
	v_mov_b32_e32 v35, v34
	s_nop 1
	v_permlane32_swap_b32_e32 v34, v35
	s_and_saveexec_b64 s[8:9], s[0:1]
	v_add_f32_e32 v34, v34, v35
	ds_write_b32 v240, v34 offset:2304
	s_or_b64 exec, exec, s[8:9]
	s_waitcnt vmcnt(5)
	v_pk_fma_f32 v[36:37], v[32:33], v[144:145], v[96:97]
	v_pk_fma_f32 v[44:45], v[30:31], v[142:143], v[94:95]
	v_pk_fma_f32 v[34:35], v[28:29], v[140:141], v[92:93]
	v_pk_fma_f32 v[42:43], v[26:27], v[138:139], v[90:91]
	v_mul_f32_e32 v30, v45, v45
	v_mul_f32_e32 v31, v37, v37
	v_mul_f32_e32 v26, v43, v43
	v_mul_f32_e32 v27, v35, v35
	v_pk_fma_f32 v[38:39], v[24:25], v[136:137], v[88:89]
	v_pk_fma_f32 v[46:47], v[22:23], v[134:135], v[86:87]
	v_fmac_f32_e32 v30, v44, v44
	v_fmac_f32_e32 v31, v36, v36
	v_fmac_f32_e32 v26, v42, v42
	v_fmac_f32_e32 v27, v34, v34
	v_mul_f32_e32 v22, v47, v47
	v_mul_f32_e32 v23, v39, v39
	s_waitcnt vmcnt(4)
	v_pk_fma_f32 v[40:41], v[20:21], v[132:133], v[84:85]
	v_pk_fma_f32 v[48:49], v[18:19], v[130:131], v[82:83]
	v_add_f32_e32 v30, v30, v31
	v_add_f32_e32 v26, v26, v27
	v_fmac_f32_e32 v22, v46, v46
	v_fmac_f32_e32 v23, v38, v38
	v_mul_f32_e32 v18, v49, v49
	v_mul_f32_e32 v19, v41, v41
	v_add_f32_e32 v26, v30, v26
	v_add_f32_e32 v22, v22, v23
	v_fmac_f32_e32 v18, v48, v48
	v_fmac_f32_e32 v19, v40, v40
	v_add_f32_e32 v22, v26, v22
	v_add_f32_e32 v18, v18, v19
	v_add_f32_e32 v18, v22, v18
	v_mov_b32_e32 v19, v18
	s_nop 1
	v_permlane16_swap_b32_e32 v18, v19
	v_add_f32_e32 v18, v18, v19
	v_mov_b32_e32 v19, v18
	s_nop 1
	v_permlane32_swap_b32_e32 v18, v19
	s_and_saveexec_b64 s[8:9], s[0:1]
	v_add_f32_e32 v18, v18, v19
	ds_write_b32 v240, v18 offset:2560
	s_or_b64 exec, exec, s[8:9]
	s_waitcnt vmcnt(1)
	v_pk_fma_f32 v[24:25], v[16:17], v[144:145], v[80:81]
	v_pk_fma_f32 v[32:33], v[14:15], v[142:143], v[78:79]
	v_pk_fma_f32 v[22:23], v[12:13], v[140:141], v[76:77]
	v_pk_fma_f32 v[30:31], v[10:11], v[138:139], v[74:75]
	v_mul_f32_e32 v14, v33, v33
	v_mul_f32_e32 v15, v25, v25
	v_mul_f32_e32 v10, v31, v31
	v_mul_f32_e32 v11, v23, v23
	v_pk_fma_f32 v[20:21], v[8:9], v[136:137], v[72:73]
	v_pk_fma_f32 v[28:29], v[6:7], v[134:135], v[70:71]
	v_fmac_f32_e32 v14, v32, v32
	v_fmac_f32_e32 v15, v24, v24
	v_fmac_f32_e32 v10, v30, v30
	v_fmac_f32_e32 v11, v22, v22
	v_mul_f32_e32 v6, v29, v29
	v_mul_f32_e32 v7, v21, v21
	s_waitcnt vmcnt(0)
	v_pk_fma_f32 v[18:19], v[4:5], v[132:133], v[68:69]
	v_pk_fma_f32 v[26:27], v[2:3], v[130:131], v[66:67]
	v_add_f32_e32 v14, v14, v15
	v_add_f32_e32 v10, v10, v11
	v_fmac_f32_e32 v6, v28, v28
	v_fmac_f32_e32 v7, v20, v20
	v_mul_f32_e32 v2, v27, v27
	v_mul_f32_e32 v3, v19, v19
	v_add_f32_e32 v10, v14, v10
	v_add_f32_e32 v6, v6, v7
	v_fmac_f32_e32 v2, v26, v26
	v_fmac_f32_e32 v3, v18, v18
	v_add_f32_e32 v6, v10, v6
	v_add_f32_e32 v2, v2, v3
	v_add_f32_e32 v2, v6, v2
	v_mov_b32_e32 v3, v2
	s_nop 1
	v_permlane16_swap_b32_e32 v2, v3
	v_add_f32_e32 v2, v2, v3
	v_mov_b32_e32 v3, v2
	s_nop 1
	v_permlane32_swap_b32_e32 v2, v3
	s_and_saveexec_b64 s[8:9], s[0:1]
	v_add_f32_e32 v2, v2, v3
	ds_write_b32 v240, v2 offset:2816
	s_or_b64 exec, exec, s[8:9]
	s_ashr_i32 s6, s57, 6
	v_and_b32_e32 v2, 31, v238
	s_waitcnt lgkmcnt(0)
	s_barrier
	v_lshl_or_b32 v4, s6, 5, v2
	v_and_b32_e32 v68, 63, v238
	v_add_u32_e32 v2, s10, v4
	v_cmp_gt_u32_e64 s[0:1], 32, v68
	v_ashrrev_i32_e32 v3, 31, v2
	s_and_saveexec_b64 s[8:9], s[0:1]
	s_cbranch_execz .LBB0_683
	v_lshl_add_u32 v5, v4, 4, 0
	v_add_u32_e32 v5, 0x20000, v5
	ds_read_b128 v[6:9], v5
	v_lshl_add_u64 v[10:11], v[2:3], 4, s[48:49]
	s_ashr_i32 s63, s62, 31
	v_lshl_add_u64 v[10:11], s[62:63], 2, v[10:11]
	s_waitcnt lgkmcnt(0)
	v_mov_b32_e32 v12, v7
	v_mov_b32_e32 v13, v8
	v_mov_b32_e32 v7, v9
	v_pk_add_f32 v[6:7], v[12:13], v[6:7]
	s_nop 0
	v_pk_add_f32 v[6:7], v[6:7], v[6:7] op_sel:[0,1] op_sel_hi:[1,0]
	global_store_dword v[10:11], v6, off sc1

.Lrwp7_exit:
.LBB0_858:
	v_mov_b32_e32 v199, v190
	v_mov_b32_e32 v161, v0
	v_mov_b32_e32 v198, v191
	s_ashr_i32 s4, s56, 3
	s_lshl_b32 s7, s56, 8
	s_add_i32 s49, s7, s73
	s_lshl_b32 s51, s6, 8
	v_lshlrev_b32_e32 v160, 2, v198
	s_mul_hi_i32 s5, s4, 0x6000
	s_mulk_i32 s4, 0x6000
	v_add_u32_e32 v118, s51, v160
	s_add_u32 s4, s69, s4
	v_add_u32_e32 v162, s49, v199
	s_addc_u32 s5, s70, s5
	v_ashrrev_i32_e32 v119, 31, v118
	v_ashrrev_i32_e32 v163, 31, v162
	v_lshl_add_u64 v[120:121], v[118:119], 2, s[4:5]
	s_lshl_b32 s10, s74, 2
	v_lshl_add_u64 v[164:165], v[118:119], 1, s[40:41]
	v_lshlrev_b64 v[118:119], 11, v[162:163]
	v_lshl_add_u64 v[120:121], v[120:121], 0, s[10:11]
	v_lshl_add_u64 v[118:119], v[164:165], 0, v[118:119]
	s_lshl_b32 s10, s74, 1
	v_lshl_add_u64 v[166:167], v[118:119], 0, s[10:11]
	v_add_co_u32_e32 v170, vcc, s78, v166
	global_load_dwordx2 v[200:201], v[166:167], off
	global_load_dwordx2 v[202:203], v[166:167], off offset:32
	global_load_dwordx2 v[204:205], v[166:167], off offset:256
	global_load_dwordx2 v[206:207], v[166:167], off offset:288
	global_load_dwordx4 v[134:137], v[120:121], off
	global_load_dwordx4 v[130:133], v[120:121], off offset:64
	global_load_dwordx4 v[126:129], v[120:121], off offset:512
	s_nop 0
	global_load_dwordx4 v[118:121], v[120:121], off offset:576
	v_addc_co_u32_e32 v171, vcc, 0, v167, vcc
	v_add_co_u32_e32 v174, vcc, s68, v166
	v_lshl_add_u64 v[168:169], v[166:167], 0, s[30:31]
	s_nop 0
	v_addc_co_u32_e32 v175, vcc, 0, v167, vcc
	v_lshl_add_u64 v[172:173], v[166:167], 0, s[34:35]
	v_lshl_add_u64 v[208:209], v[166:167], 0, s[36:37]
	v_add_co_u32_e32 v166, vcc, s77, v166
	v_add_u32_e32 v218, s73, v199
	s_nop 0
	v_addc_co_u32_e32 v167, vcc, 0, v167, vcc
	global_load_dwordx2 v[188:189], v[170:171], off
	global_load_dwordx2 v[186:187], v[168:169], off offset:32
	global_load_dwordx2 v[184:185], v[168:169], off offset:256
	global_load_dwordx2 v[182:183], v[168:169], off offset:288
	global_load_dwordx2 v[180:181], v[174:175], off
	global_load_dwordx2 v[178:179], v[172:173], off offset:32
	global_load_dwordx2 v[176:177], v[172:173], off offset:256
	s_nop 0
	global_load_dwordx2 v[174:175], v[172:173], off offset:288
	s_nop 0
	global_load_dwordx2 v[172:173], v[166:167], off
	global_load_dwordx2 v[170:171], v[208:209], off offset:32
	global_load_dwordx2 v[168:169], v[208:209], off offset:256
	s_nop 0
	global_load_dwordx2 v[166:167], v[208:209], off offset:288
	v_readfirstlane_b32 s57, v161
	v_cmp_eq_u32_e64 s[4:5], 0, v198
	s_cmp_lg_u64 s[26:27], 0
	s_cbranch_scc0 .Lp7_nobar
	s_barrier
.Lp7_nobar:
	s_waitcnt vmcnt(0)
	v_and_b32_e32 v209, 0xffff0000, v200
	v_lshlrev_b32_e32 v208, 16, v200
	v_and_b32_e32 v211, 0xffff0000, v201
	v_lshlrev_b32_e32 v210, 16, v201
	v_and_b32_e32 v201, 0xffff0000, v202
	v_lshlrev_b32_e32 v200, 16, v202
	v_and_b32_e32 v213, 0xffff0000, v203
	v_lshlrev_b32_e32 v212, 16, v203
	v_pk_fma_f32 v[144:145], v[144:145], v[136:137], v[210:211]
	v_pk_fma_f32 v[142:143], v[142:143], v[134:135], v[208:209]
	v_pk_fma_f32 v[140:141], v[140:141], v[132:133], v[212:213]
	v_pk_fma_f32 v[138:139], v[138:139], v[130:131], v[200:201]
	v_and_b32_e32 v203, 0xffff0000, v204
	v_lshlrev_b32_e32 v202, 16, v204
	v_and_b32_e32 v215, 0xffff0000, v205
	v_lshlrev_b32_e32 v214, 16, v205
	v_and_b32_e32 v205, 0xffff0000, v206
	v_lshlrev_b32_e32 v204, 16, v206
	v_and_b32_e32 v217, 0xffff0000, v207
	v_lshlrev_b32_e32 v216, 16, v207
	v_mul_f32_e32 v200, v143, v143
	v_mul_f32_e32 v201, v145, v145
	v_mul_f32_e32 v206, v139, v139
	v_mul_f32_e32 v207, v141, v141
	v_fmac_f32_e32 v200, v142, v142
	v_fmac_f32_e32 v201, v144, v144
	v_fmac_f32_e32 v206, v138, v138
	v_fmac_f32_e32 v207, v140, v140
	v_add_f32_e32 v200, v200, v201
	v_add_f32_e32 v201, v206, v207
	v_pk_fma_f32 v[124:125], v[124:125], v[128:129], v[214:215]
	v_pk_fma_f32 v[122:123], v[122:123], v[126:127], v[202:203]
	v_add_f32_e32 v200, v200, v201
	v_mul_f32_e32 v201, v123, v123
	v_mul_f32_e32 v202, v125, v125
	v_fmac_f32_e32 v201, v122, v122
	v_fmac_f32_e32 v202, v124, v124
	v_add_f32_e32 v201, v201, v202
	v_pk_fma_f32 v[116:117], v[116:117], v[120:121], v[216:217]
	v_pk_fma_f32 v[114:115], v[114:115], v[118:119], v[204:205]
	v_add_f32_e32 v200, v200, v201
	v_mul_f32_e32 v201, v115, v115
	v_mul_f32_e32 v202, v117, v117
	v_fmac_f32_e32 v201, v114, v114
	v_fmac_f32_e32 v202, v116, v116
	v_add_f32_e32 v201, v201, v202
	v_add_f32_e32 v200, v200, v201
	v_mov_b32_e32 v201, v200
	s_nop 1
	v_permlane16_swap_b32_e32 v200, v201
	v_add_f32_e32 v201, v200, v201
	v_mov_b32_e32 v202, v201
	s_nop 1
	v_permlane32_swap_b32_e32 v201, v202
	v_lshl_add_u32 v200, v218, 4, s81
	s_and_saveexec_b64 s[8:9], s[4:5]
	v_add_f32_e32 v201, v201, v202
	ds_write_b32 v200, v201
	s_or_b64 exec, exec, s[8:9]
	v_and_b32_e32 v203, 0xffff0000, v188
	v_and_b32_e32 v205, 0xffff0000, v189
	v_lshlrev_b32_e32 v202, 16, v188
	v_lshlrev_b32_e32 v204, 16, v189
	v_pk_fma_f32 v[112:113], v[112:113], v[136:137], v[204:205]
	v_pk_fma_f32 v[110:111], v[110:111], v[134:135], v[202:203]
	v_and_b32_e32 v189, 0xffff0000, v186
	v_and_b32_e32 v207, 0xffff0000, v187
	v_lshlrev_b32_e32 v188, 16, v186
	v_lshlrev_b32_e32 v206, 16, v187
	v_and_b32_e32 v187, 0xffff0000, v184
	v_and_b32_e32 v209, 0xffff0000, v185
	v_lshlrev_b32_e32 v186, 16, v184
	v_lshlrev_b32_e32 v208, 16, v185
	v_and_b32_e32 v185, 0xffff0000, v182
	v_and_b32_e32 v211, 0xffff0000, v183
	v_lshlrev_b32_e32 v184, 16, v182
	v_lshlrev_b32_e32 v210, 16, v183
	v_mul_f32_e32 v182, v111, v111
	v_mul_f32_e32 v183, v113, v113
	v_fmac_f32_e32 v182, v110, v110
	v_fmac_f32_e32 v183, v112, v112
	v_pk_fma_f32 v[108:109], v[108:109], v[132:133], v[206:207]
	v_pk_fma_f32 v[106:107], v[106:107], v[130:131], v[188:189]
	v_add_f32_e32 v182, v182, v183
	v_mul_f32_e32 v183, v107, v107
	v_mul_f32_e32 v188, v109, v109
	v_fmac_f32_e32 v183, v106, v106
	v_fmac_f32_e32 v188, v108, v108
	v_add_f32_e32 v183, v183, v188
	v_pk_fma_f32 v[104:105], v[104:105], v[128:129], v[208:209]
	v_pk_fma_f32 v[102:103], v[102:103], v[126:127], v[186:187]
	v_add_f32_e32 v182, v182, v183
	v_mul_f32_e32 v183, v103, v103
	v_mul_f32_e32 v186, v105, v105
	v_fmac_f32_e32 v183, v102, v102
	v_fmac_f32_e32 v186, v104, v104
	v_add_f32_e32 v183, v183, v186
	v_pk_fma_f32 v[100:101], v[100:101], v[120:121], v[210:211]
	v_pk_fma_f32 v[98:99], v[98:99], v[118:119], v[184:185]
	v_add_f32_e32 v182, v182, v183
	v_mul_f32_e32 v183, v99, v99
	v_mul_f32_e32 v184, v101, v101
	v_fmac_f32_e32 v183, v98, v98
	v_fmac_f32_e32 v184, v100, v100
	v_add_f32_e32 v183, v183, v184
	v_add_f32_e32 v182, v182, v183
	v_mov_b32_e32 v183, v182
	s_nop 1
	v_permlane16_swap_b32_e32 v182, v183
	v_add_f32_e32 v182, v182, v183
	v_mov_b32_e32 v183, v182
	s_nop 1
	v_permlane32_swap_b32_e32 v182, v183
	s_and_saveexec_b64 s[8:9], s[4:5]
	v_add_f32_e32 v182, v182, v183
	ds_write_b32 v200, v182 offset:256
	s_or_b64 exec, exec, s[8:9]
	v_and_b32_e32 v183, 0xffff0000, v180
	v_and_b32_e32 v185, 0xffff0000, v181
	v_lshlrev_b32_e32 v182, 16, v180
	v_lshlrev_b32_e32 v184, 16, v181
	v_pk_fma_f32 v[96:97], v[96:97], v[136:137], v[184:185]
	v_pk_fma_f32 v[94:95], v[94:95], v[134:135], v[182:183]
	v_and_b32_e32 v181, 0xffff0000, v178
	v_and_b32_e32 v187, 0xffff0000, v179
	v_lshlrev_b32_e32 v180, 16, v178
	v_lshlrev_b32_e32 v186, 16, v179
	v_and_b32_e32 v179, 0xffff0000, v176
	v_and_b32_e32 v189, 0xffff0000, v177
	v_lshlrev_b32_e32 v178, 16, v176
	v_lshlrev_b32_e32 v188, 16, v177
	v_and_b32_e32 v177, 0xffff0000, v174
	v_and_b32_e32 v203, 0xffff0000, v175
	v_lshlrev_b32_e32 v176, 16, v174
	v_lshlrev_b32_e32 v202, 16, v175
	v_mul_f32_e32 v174, v95, v95
	v_mul_f32_e32 v175, v97, v97
	v_fmac_f32_e32 v174, v94, v94
	v_fmac_f32_e32 v175, v96, v96
	v_pk_fma_f32 v[92:93], v[92:93], v[132:133], v[186:187]
	v_pk_fma_f32 v[90:91], v[90:91], v[130:131], v[180:181]
	v_add_f32_e32 v174, v174, v175
	v_mul_f32_e32 v175, v91, v91
	v_mul_f32_e32 v180, v93, v93
	v_fmac_f32_e32 v175, v90, v90
	v_fmac_f32_e32 v180, v92, v92
	v_add_f32_e32 v175, v175, v180
	v_pk_fma_f32 v[88:89], v[88:89], v[128:129], v[188:189]
	v_pk_fma_f32 v[86:87], v[86:87], v[126:127], v[178:179]
	v_add_f32_e32 v174, v174, v175
	v_mul_f32_e32 v175, v87, v87
	v_mul_f32_e32 v178, v89, v89
	v_fmac_f32_e32 v175, v86, v86
	v_fmac_f32_e32 v178, v88, v88
	v_add_f32_e32 v175, v175, v178
	v_pk_fma_f32 v[84:85], v[84:85], v[120:121], v[202:203]
	v_pk_fma_f32 v[82:83], v[82:83], v[118:119], v[176:177]
	v_add_f32_e32 v174, v174, v175
	v_mul_f32_e32 v175, v83, v83
	v_mul_f32_e32 v176, v85, v85
	v_fmac_f32_e32 v175, v82, v82
	v_fmac_f32_e32 v176, v84, v84
	v_add_f32_e32 v175, v175, v176
	v_add_f32_e32 v174, v174, v175
	v_mov_b32_e32 v175, v174
	s_nop 1
	v_permlane16_swap_b32_e32 v174, v175
	v_add_f32_e32 v174, v174, v175
	v_mov_b32_e32 v175, v174
	s_nop 1
	v_permlane32_swap_b32_e32 v174, v175
	s_and_saveexec_b64 s[8:9], s[4:5]
	v_add_f32_e32 v174, v174, v175
	ds_write_b32 v200, v174 offset:512
	s_or_b64 exec, exec, s[8:9]
	v_and_b32_e32 v175, 0xffff0000, v172
	v_and_b32_e32 v177, 0xffff0000, v173
	v_lshlrev_b32_e32 v174, 16, v172
	v_lshlrev_b32_e32 v176, 16, v173
	v_pk_fma_f32 v[80:81], v[80:81], v[136:137], v[176:177]
	v_pk_fma_f32 v[78:79], v[78:79], v[134:135], v[174:175]
	v_and_b32_e32 v173, 0xffff0000, v170
	v_and_b32_e32 v179, 0xffff0000, v171
	v_lshlrev_b32_e32 v172, 16, v170
	v_lshlrev_b32_e32 v178, 16, v171
	v_and_b32_e32 v171, 0xffff0000, v168
	v_and_b32_e32 v181, 0xffff0000, v169
	v_lshlrev_b32_e32 v170, 16, v168
	v_lshlrev_b32_e32 v180, 16, v169
	v_and_b32_e32 v169, 0xffff0000, v166
	v_and_b32_e32 v183, 0xffff0000, v167
	v_lshlrev_b32_e32 v168, 16, v166
	v_lshlrev_b32_e32 v182, 16, v167
	v_mul_f32_e32 v166, v79, v79
	v_mul_f32_e32 v167, v81, v81
	v_fmac_f32_e32 v166, v78, v78
	v_fmac_f32_e32 v167, v80, v80
	v_pk_fma_f32 v[76:77], v[76:77], v[132:133], v[178:179]
	v_pk_fma_f32 v[74:75], v[74:75], v[130:131], v[172:173]
	v_add_f32_e32 v166, v166, v167
	v_mul_f32_e32 v167, v75, v75
	v_mul_f32_e32 v172, v77, v77
	v_fmac_f32_e32 v167, v74, v74
	v_fmac_f32_e32 v172, v76, v76
	v_add_f32_e32 v167, v167, v172
	v_pk_fma_f32 v[72:73], v[72:73], v[128:129], v[180:181]
	v_pk_fma_f32 v[70:71], v[70:71], v[126:127], v[170:171]
	v_add_f32_e32 v166, v166, v167
	v_mul_f32_e32 v167, v71, v71
	v_mul_f32_e32 v170, v73, v73
	v_fmac_f32_e32 v167, v70, v70
	v_fmac_f32_e32 v170, v72, v72
	v_add_f32_e32 v167, v167, v170
	v_pk_fma_f32 v[68:69], v[68:69], v[120:121], v[182:183]
	v_pk_fma_f32 v[66:67], v[66:67], v[118:119], v[168:169]
	v_add_f32_e32 v166, v166, v167
	v_mul_f32_e32 v167, v67, v67
	v_mul_f32_e32 v168, v69, v69
	v_fmac_f32_e32 v167, v66, v66
	v_fmac_f32_e32 v168, v68, v68
	v_add_f32_e32 v167, v167, v168
	v_add_f32_e32 v166, v166, v167
	v_mov_b32_e32 v167, v166
	s_nop 1
	v_permlane16_swap_b32_e32 v166, v167
	v_add_f32_e32 v166, v166, v167
	v_mov_b32_e32 v167, v166
	s_nop 1
	v_permlane32_swap_b32_e32 v166, v167
	s_and_saveexec_b64 s[8:9], s[4:5]
	v_add_f32_e32 v166, v166, v167
	ds_write_b32 v200, v166 offset:768
	s_or_b64 exec, exec, s[8:9]
	v_lshlrev_b64 v[162:163], 11, v[162:163]
	v_lshl_add_u64 v[162:163], v[164:165], 0, v[162:163]
	v_lshl_add_u64 v[162:163], v[162:163], 0, s[10:11]
	v_add_co_u32_e32 v168, vcc, 0x40000, v162
	v_lshl_add_u64 v[164:165], v[162:163], 0, s[38:39]
	s_nop 0
	v_addc_co_u32_e32 v169, vcc, 0, v163, vcc
	global_load_dwordx2 v[166:167], v[164:165], off offset:32
	global_load_dwordx2 v[170:171], v[164:165], off offset:256
	global_load_dwordx2 v[202:203], v[168:169], off
	global_load_dwordx2 v[204:205], v[164:165], off offset:288
	v_add_co_u32_e32 v168, vcc, s86, v162
	v_lshl_add_u64 v[164:165], v[162:163], 0, s[42:43]
	s_nop 0
	v_addc_co_u32_e32 v169, vcc, 0, v163, vcc
	v_add_co_u32_e32 v174, vcc, s87, v162
	v_lshl_add_u64 v[172:173], v[162:163], 0, s[44:45]
	s_nop 0
	v_addc_co_u32_e32 v175, vcc, 0, v163, vcc
	v_add_co_u32_e32 v176, vcc, s88, v162
	v_lshl_add_u64 v[206:207], v[162:163], 0, s[46:47]
	s_nop 0
	v_addc_co_u32_e32 v177, vcc, 0, v163, vcc
	global_load_dwordx2 v[188:189], v[168:169], off
	global_load_dwordx2 v[186:187], v[164:165], off offset:32
	global_load_dwordx2 v[184:185], v[164:165], off offset:256
	s_nop 0
	global_load_dwordx2 v[164:165], v[164:165], off offset:288
	s_nop 0
	global_load_dwordx2 v[182:183], v[174:175], off
	global_load_dwordx2 v[180:181], v[172:173], off offset:32
	global_load_dwordx2 v[168:169], v[172:173], off offset:256
	global_load_dwordx2 v[162:163], v[172:173], off offset:288
	global_load_dwordx2 v[178:179], v[176:177], off
	s_nop 0
	global_load_dwordx2 v[176:177], v[206:207], off offset:32
	global_load_dwordx2 v[174:175], v[206:207], off offset:256
	global_load_dwordx2 v[172:173], v[206:207], off offset:288
	s_waitcnt vmcnt(15)
	v_and_b32_e32 v207, 0xffff0000, v166
	v_lshlrev_b32_e32 v206, 16, v166
	v_and_b32_e32 v209, 0xffff0000, v167
	v_lshlrev_b32_e32 v208, 16, v167
	s_waitcnt vmcnt(14)
	v_and_b32_e32 v167, 0xffff0000, v170
	v_lshlrev_b32_e32 v166, 16, v170
	v_and_b32_e32 v211, 0xffff0000, v171
	v_lshlrev_b32_e32 v210, 16, v171
	s_waitcnt vmcnt(13)
	v_and_b32_e32 v171, 0xffff0000, v202
	v_lshlrev_b32_e32 v170, 16, v202
	v_and_b32_e32 v213, 0xffff0000, v203
	v_lshlrev_b32_e32 v212, 16, v203
	s_waitcnt vmcnt(12)
	v_and_b32_e32 v203, 0xffff0000, v204
	v_lshlrev_b32_e32 v202, 16, v204
	v_pk_fma_f32 v[64:65], v[64:65], v[132:133], v[208:209]
	v_pk_fma_f32 v[62:63], v[62:63], v[130:131], v[206:207]
	v_pk_fma_f32 v[56:57], v[56:57], v[128:129], v[210:211]
	v_pk_fma_f32 v[54:55], v[54:55], v[126:127], v[166:167]
	v_pk_fma_f32 v[166:167], v[60:61], v[136:137], v[212:213]
	v_pk_fma_f32 v[170:171], v[58:59], v[134:135], v[170:171]
	v_and_b32_e32 v215, 0xffff0000, v205
	v_lshlrev_b32_e32 v214, 16, v205
	v_mul_f32_e32 v58, v63, v63
	v_mul_f32_e32 v59, v65, v65
	v_mul_f32_e32 v60, v55, v55
	v_mul_f32_e32 v61, v57, v57
	v_pk_fma_f32 v[50:51], v[50:51], v[118:119], v[202:203]
	v_mul_f32_e32 v201, v171, v171
	v_mul_f32_e32 v202, v167, v167
	v_pk_fma_f32 v[52:53], v[52:53], v[120:121], v[214:215]
	v_fmac_f32_e32 v58, v62, v62
	v_fmac_f32_e32 v59, v64, v64
	v_fmac_f32_e32 v60, v54, v54
	v_fmac_f32_e32 v61, v56, v56
	v_fmac_f32_e32 v201, v170, v170
	v_fmac_f32_e32 v202, v166, v166
	v_mul_f32_e32 v203, v51, v51
	v_mul_f32_e32 v204, v53, v53
	v_add_f32_e32 v58, v58, v59
	v_add_f32_e32 v59, v60, v61
	v_add_f32_e32 v60, v201, v202
	v_fmac_f32_e32 v203, v50, v50
	v_fmac_f32_e32 v204, v52, v52
	v_add_f32_e32 v58, v60, v58
	v_add_f32_e32 v61, v203, v204
	v_add_f32_e32 v58, v58, v59
	v_add_f32_e32 v58, v58, v61
	v_mov_b32_e32 v59, v58
	s_nop 1
	v_permlane16_swap_b32_e32 v58, v59
	v_add_f32_e32 v58, v58, v59
	v_mov_b32_e32 v59, v58
	s_nop 1
	v_permlane32_swap_b32_e32 v58, v59
	s_and_saveexec_b64 s[8:9], s[4:5]
	v_add_f32_e32 v58, v58, v59
	ds_write_b32 v200, v58 offset:2048
	s_or_b64 exec, exec, s[8:9]
	s_waitcnt vmcnt(11)
	v_and_b32_e32 v59, 0xffff0000, v188
	v_and_b32_e32 v61, 0xffff0000, v189
	v_lshlrev_b32_e32 v58, 16, v188
	v_lshlrev_b32_e32 v60, 16, v189
	s_waitcnt vmcnt(10)
	v_and_b32_e32 v189, 0xffff0000, v186
	v_and_b32_e32 v203, 0xffff0000, v187
	v_lshlrev_b32_e32 v188, 16, v186
	v_lshlrev_b32_e32 v202, 16, v187
	s_waitcnt vmcnt(9)
	v_and_b32_e32 v187, 0xffff0000, v184
	v_and_b32_e32 v205, 0xffff0000, v185
	v_lshlrev_b32_e32 v186, 16, v184
	v_lshlrev_b32_e32 v204, 16, v185
	s_waitcnt vmcnt(8)
	v_and_b32_e32 v185, 0xffff0000, v164
	v_and_b32_e32 v207, 0xffff0000, v165
	v_lshlrev_b32_e32 v184, 16, v164
	v_lshlrev_b32_e32 v206, 16, v165
	v_pk_fma_f32 v[48:49], v[48:49], v[136:137], v[60:61]
	v_pk_fma_f32 v[60:61], v[44:45], v[132:133], v[202:203]
	v_pk_fma_f32 v[164:165], v[42:43], v[130:131], v[188:189]
	v_pk_fma_f32 v[58:59], v[46:47], v[134:135], v[58:59]
	v_mul_f32_e32 v42, v165, v165
	v_mul_f32_e32 v43, v61, v61
	v_mul_f32_e32 v46, v59, v59
	v_mul_f32_e32 v47, v49, v49
	v_fmac_f32_e32 v42, v164, v164
	v_fmac_f32_e32 v43, v60, v60
	v_pk_fma_f32 v[40:41], v[40:41], v[128:129], v[204:205]
	v_pk_fma_f32 v[38:39], v[38:39], v[126:127], v[186:187]
	v_fmac_f32_e32 v46, v58, v58
	v_fmac_f32_e32 v47, v48, v48
	v_add_f32_e32 v42, v42, v43
	v_mul_f32_e32 v43, v39, v39
	v_mul_f32_e32 v44, v41, v41
	v_add_f32_e32 v46, v46, v47
	v_fmac_f32_e32 v43, v38, v38
	v_fmac_f32_e32 v44, v40, v40
	v_add_f32_e32 v42, v46, v42
	v_add_f32_e32 v43, v43, v44
	v_pk_fma_f32 v[36:37], v[36:37], v[120:121], v[206:207]
	v_pk_fma_f32 v[34:35], v[34:35], v[118:119], v[184:185]
	v_add_f32_e32 v42, v42, v43
	v_mul_f32_e32 v43, v35, v35
	v_mul_f32_e32 v44, v37, v37
	v_fmac_f32_e32 v43, v34, v34
	v_fmac_f32_e32 v44, v36, v36
	v_add_f32_e32 v43, v43, v44
	v_add_f32_e32 v42, v42, v43
	v_mov_b32_e32 v43, v42
	s_nop 1
	v_permlane16_swap_b32_e32 v42, v43
	v_add_f32_e32 v42, v42, v43
	v_mov_b32_e32 v43, v42
	s_nop 1
	v_permlane32_swap_b32_e32 v42, v43
	s_and_saveexec_b64 s[8:9], s[4:5]
	v_add_f32_e32 v42, v42, v43
	ds_write_b32 v200, v42 offset:2304
	s_or_b64 exec, exec, s[8:9]
	s_waitcnt vmcnt(7)
	v_and_b32_e32 v43, 0xffff0000, v182
	v_and_b32_e32 v45, 0xffff0000, v183
	v_lshlrev_b32_e32 v42, 16, v182
	v_lshlrev_b32_e32 v44, 16, v183
	s_waitcnt vmcnt(6)
	v_and_b32_e32 v183, 0xffff0000, v180
	v_and_b32_e32 v185, 0xffff0000, v181
	v_lshlrev_b32_e32 v182, 16, v180
	v_lshlrev_b32_e32 v184, 16, v181
	s_waitcnt vmcnt(5)
	v_and_b32_e32 v181, 0xffff0000, v168
	v_and_b32_e32 v187, 0xffff0000, v169
	v_lshlrev_b32_e32 v180, 16, v168
	v_lshlrev_b32_e32 v186, 16, v169
	s_waitcnt vmcnt(4)
	v_and_b32_e32 v189, 0xffff0000, v162
	v_and_b32_e32 v203, 0xffff0000, v163
	v_lshlrev_b32_e32 v188, 16, v162
	v_lshlrev_b32_e32 v202, 16, v163
	v_pk_fma_f32 v[162:163], v[28:29], v[132:133], v[184:185]
	v_pk_fma_f32 v[168:169], v[26:27], v[130:131], v[182:183]
	v_mul_f32_e32 v27, v163, v163
	v_mul_f32_e32 v26, v169, v169
	v_fmac_f32_e32 v26, v168, v168
	v_fmac_f32_e32 v27, v162, v162
	v_pk_fma_f32 v[24:25], v[24:25], v[128:129], v[186:187]
	v_pk_fma_f32 v[22:23], v[22:23], v[126:127], v[180:181]
	v_pk_fma_f32 v[32:33], v[32:33], v[136:137], v[44:45]
	v_pk_fma_f32 v[46:47], v[30:31], v[134:135], v[42:43]
	v_add_f32_e32 v26, v26, v27
	v_mul_f32_e32 v27, v23, v23
	v_mul_f32_e32 v28, v25, v25
	v_mul_f32_e32 v30, v47, v47
	v_mul_f32_e32 v31, v33, v33
	v_fmac_f32_e32 v27, v22, v22
	v_fmac_f32_e32 v28, v24, v24
	v_fmac_f32_e32 v30, v46, v46
	v_fmac_f32_e32 v31, v32, v32
	v_add_f32_e32 v27, v27, v28
	v_pk_fma_f32 v[28:29], v[20:21], v[120:121], v[202:203]
	v_pk_fma_f32 v[44:45], v[18:19], v[118:119], v[188:189]
	v_add_f32_e32 v30, v30, v31
	v_mul_f32_e32 v18, v45, v45
	v_mul_f32_e32 v19, v29, v29
	v_add_f32_e32 v26, v30, v26
	v_fmac_f32_e32 v18, v44, v44
	v_fmac_f32_e32 v19, v28, v28
	v_add_f32_e32 v26, v26, v27
	v_add_f32_e32 v18, v18, v19
	v_add_f32_e32 v18, v26, v18
	v_mov_b32_e32 v19, v18
	s_nop 1
	v_permlane16_swap_b32_e32 v18, v19
	v_add_f32_e32 v18, v18, v19
	v_mov_b32_e32 v19, v18
	s_nop 1
	v_permlane32_swap_b32_e32 v18, v19
	s_and_saveexec_b64 s[8:9], s[4:5]
	v_add_f32_e32 v18, v18, v19
	ds_write_b32 v200, v18 offset:2560
	s_or_b64 exec, exec, s[8:9]
	s_waitcnt vmcnt(3)
	v_and_b32_e32 v19, 0xffff0000, v178
	v_and_b32_e32 v21, 0xffff0000, v179
	v_lshlrev_b32_e32 v18, 16, v178
	v_lshlrev_b32_e32 v20, 16, v179
	s_waitcnt vmcnt(2)
	v_and_b32_e32 v27, 0xffff0000, v176
	v_and_b32_e32 v31, 0xffff0000, v177
	v_lshlrev_b32_e32 v26, 16, v176
	v_lshlrev_b32_e32 v30, 16, v177
	s_waitcnt vmcnt(1)
	v_and_b32_e32 v177, 0xffff0000, v174
	v_and_b32_e32 v179, 0xffff0000, v175
	v_lshlrev_b32_e32 v176, 16, v174
	v_lshlrev_b32_e32 v178, 16, v175
	v_pk_fma_f32 v[42:43], v[16:17], v[136:137], v[20:21]
	v_pk_fma_f32 v[134:135], v[14:15], v[134:135], v[18:19]
	v_pk_fma_f32 v[132:133], v[12:13], v[132:133], v[30:31]
	v_pk_fma_f32 v[130:131], v[10:11], v[130:131], v[26:27]
	s_waitcnt vmcnt(0)
	v_and_b32_e32 v175, 0xffff0000, v172
	v_and_b32_e32 v181, 0xffff0000, v173
	v_lshlrev_b32_e32 v174, 16, v172
	v_lshlrev_b32_e32 v180, 16, v173
	v_mul_f32_e32 v14, v135, v135
	v_mul_f32_e32 v15, v43, v43
	v_mul_f32_e32 v10, v131, v131
	v_mul_f32_e32 v11, v133, v133
	v_pk_fma_f32 v[18:19], v[8:9], v[128:129], v[178:179]
	v_pk_fma_f32 v[20:21], v[6:7], v[126:127], v[176:177]
	v_fmac_f32_e32 v14, v134, v134
	v_fmac_f32_e32 v15, v42, v42
	v_fmac_f32_e32 v10, v130, v130
	v_fmac_f32_e32 v11, v132, v132
	v_mul_f32_e32 v6, v21, v21
	v_mul_f32_e32 v7, v19, v19
	v_pk_fma_f32 v[26:27], v[4:5], v[120:121], v[180:181]
	v_pk_fma_f32 v[30:31], v[2:3], v[118:119], v[174:175]
	v_add_f32_e32 v14, v14, v15
	v_add_f32_e32 v10, v10, v11
	v_fmac_f32_e32 v6, v20, v20
	v_fmac_f32_e32 v7, v18, v18
	v_mul_f32_e32 v2, v31, v31
	v_mul_f32_e32 v3, v27, v27
	v_add_f32_e32 v10, v14, v10
	v_add_f32_e32 v6, v6, v7
	v_fmac_f32_e32 v2, v30, v30
	v_fmac_f32_e32 v3, v26, v26
	v_add_f32_e32 v6, v10, v6
	v_add_f32_e32 v2, v2, v3
	v_add_f32_e32 v2, v6, v2
	v_mov_b32_e32 v3, v2
	s_nop 1
	v_permlane16_swap_b32_e32 v2, v3
	v_add_f32_e32 v2, v2, v3
	v_mov_b32_e32 v3, v2
	s_nop 1
	v_permlane32_swap_b32_e32 v2, v3
	s_and_saveexec_b64 s[8:9], s[4:5]
	v_add_f32_e32 v2, v2, v3
	ds_write_b32 v200, v2 offset:2816
	s_or_b64 exec, exec, s[8:9]
	s_ashr_i32 s4, s57, 1
	v_mov_b32_e32 v2, s4
	s_waitcnt lgkmcnt(0)
	s_barrier
	v_bfi_b32 v4, s83, v2, v161
	v_and_b32_e32 v5, 63, v161
	v_add_u32_e32 v2, s7, v4
	v_cmp_gt_u32_e64 s[8:9], 32, v5
	v_ashrrev_i32_e32 v3, 31, v2
	s_and_saveexec_b64 s[4:5], s[8:9]
	s_cbranch_execz .LBB0_876
	v_lshl_add_u32 v6, v4, 4, 0
	v_add_u32_e32 v6, 0x20000, v6
	ds_read_b128 v[6:9], v6
	v_lshl_add_u64 v[10:11], v[2:3], 4, s[16:17]
	s_ashr_i32 s7, s6, 31
	v_lshl_add_u64 v[10:11], s[6:7], 2, v[10:11]
	s_waitcnt lgkmcnt(0)
	v_mov_b32_e32 v12, v7
	v_mov_b32_e32 v13, v8
	v_mov_b32_e32 v7, v9
	v_pk_add_f32 v[6:7], v[12:13], v[6:7]
	s_nop 0
	v_pk_add_f32 v[6:7], v[6:7], v[6:7] op_sel:[0,1] op_sel_hi:[1,0]
	global_store_dword v[10:11], v6, off sc1
